# P1 row loop: next row of x prefetched by LDS-DMA into a per-wave LDS buffer (plus weight table in registers and DPP sums)
# speedup vs baseline: 1.0097x; 1.0053x over previous
; #define GAS __attribute__((address_space(1)))
; template <int LO, int HI> __global__ void __launch_bounds__(NWAVES * 64, 2) fox_fwd(Args args) {
;     ...
;         const int m0 = gw * 16, b = m0 / T;
;         f32x4 gm[4], sh[4];
; #pragma unroll
;         for (int j = 0; j < 4; ++j) { const int col = P1COL(j); const f32x4 g = *(const f32x4*)(norm_g + col), scl = *(const f32x4*)(ADA + b * 3072 + 1024 + col);
;             gm[j] = g * (scl + 1.0f); sh[j] = *(const f32x4*)(ADA + b * 3072 + col); }
;         const float bfv = b_f[lane & 7]; f32x4 lsq[4];
; #pragma unroll
;         for (int k = 0; k < 4; ++k) lsq[k] = (f32x4){0.f, 0.f, 0.f, 0.f};
;         for (int r = 0; r < 16; ++r) { const int m = m0 + r;
;             const GAS float* xr = (const GAS float*)(x + (size_t)m * D);
;             f32x4 v[4]; float s2 = 0.f;
; #pragma unroll
;             for (int j = 0; j < 4; ++j) { v[j] = *(const GAS f32x4*)(xr + P1COL(j)); s2 += (v[j][0] * v[j][0] + v[j][1] * v[j][1]) + (v[j][2] * v[j][2] + v[j][3] * v[j][3]); }
;             const float rstd = 1.0f / sqrtf(wave_sum(s2) * (1.0f / D) + EPS);
.LBB0_130:
	s_or_b64 exec, exec, s[8:9]
	s_ashr_i32 s43, s15, 6
	s_lshl_b32 s8, s14, 3
	s_add_i32 s33, s8, s43
	s_ashr_i32 s8, s33, 31
	s_lshr_b32 s8, s8, 24
	s_add_i32 s8, s33, s8
	s_ashr_i32 s44, s8, 8
	s_mul_i32 s8, s44, 0xc00
	s_ashr_i32 s9, s8, 31
	s_lshl_b64 s[8:9], s[8:9], 2
	s_add_u32 s8, s26, s8
	s_addc_u32 s9, s27, s9
	s_add_u32 s10, s8, 0x1000
	s_addc_u32 s11, s9, 0
	s_lshl_b32 s28, s33, 4
	s_ashr_i32 s29, s28, 31
	s_lshl_b64 s[12:13], s[28:29], 12
	v_and_b32_e32 v1, 63, v34
	s_waitcnt lgkmcnt(0)
	s_add_u32 s30, s6, s12
	v_lshlrev_b32_e32 v54, 5, v1
	s_addc_u32 s31, s7, s13
	s_barrier
	global_load_dwordx4 v[26:29], v54, s[30:31]
	global_load_dwordx4 v[18:21], v54, s[30:31] offset:16
	global_load_dwordx4 v[22:25], v54, s[30:31] offset:2064
	global_load_dwordx4 v[30:33], v54, s[30:31] offset:2048
	global_load_dwordx4 v[38:41], v54, s[10:11] offset:16
	global_load_dwordx4 v[42:45], v54, s[10:11]
	v_mbcnt_lo_u32_b32 v3, -1, 0
	v_and_b32_e32 v2, 7, v34
	v_mbcnt_hi_u32_b32 v35, -1, v3
	v_or_b32_e32 v3, 0x800, v54
	v_lshlrev_b32_e32 v2, 2, v2
	global_load_dwordx4 v[46:49], v3, s[10:11] offset:16
	global_load_dwordx4 v[50:53], v3, s[10:11]
	global_load_dwordx4 v[58:61], v54, s[20:21] offset:16
	global_load_dwordx4 v[62:65], v54, s[20:21]
	global_load_dwordx4 v[74:77], v54, s[20:21] offset:2064
	global_load_dwordx4 v[78:81], v54, s[20:21] offset:2048
	global_load_dword v71, v2, s[4:5]
	v_xor_b32_e32 v83, 16, v35
	v_and_b32_e32 v68, 64, v35
	v_mov_b32_e32 v37, 0
	v_lshlrev_b32_e32 v36, 4, v1
	v_xor_b32_e32 v4, 1, v35
	v_add_u32_e32 v87, 64, v68
	s_mov_b64 s[12:13], 0x2000000
	v_xor_b32_e32 v5, 2, v35
	v_lshl_add_u64 v[2:3], s[26:27], 0, v[36:37]
	v_cmp_lt_i32_e32 vcc, v4, v87
	v_lshl_add_u64 v[56:57], v[2:3], 0, s[12:13]
	v_xor_b32_e32 v55, 4, v35
	v_cndmask_b32_e32 v2, v35, v4, vcc
	v_cmp_lt_i32_e32 vcc, v5, v87
	v_lshlrev_b32_e32 v165, 2, v2
	v_xor_b32_e32 v73, 8, v35
	v_cndmask_b32_e32 v88, v35, v5, vcc
	global_load_dwordx4 v[2:5], v54, s[8:9] offset:16
	global_load_dwordx4 v[6:9], v54, s[8:9]
	v_lshlrev_b32_e32 v169, 2, v88
	v_cmp_lt_i32_e32 vcc, v55, v87
	v_xor_b32_e32 v86, 32, v35
	v_mov_b32_e32 v69, 0x358637bd
	v_cndmask_b32_e32 v55, v35, v55, vcc
	v_lshlrev_b32_e32 v168, 2, v55
	v_cmp_lt_i32_e32 vcc, v73, v87
	s_mov_b32 s45, 0xf800000
	v_mov_b32_e32 v70, 0x260
	v_cndmask_b32_e32 v73, v35, v73, vcc
	v_lshlrev_b32_e32 v167, 2, v73
	v_cmp_lt_i32_e32 vcc, v83, v87
	s_lshl_b64 s[34:35], s[28:29], 11
	v_add_u32_e32 v72, 0, v54
	s_or_b32 s36, s28, 1
	s_ashr_i32 s37, s36, 31
	v_cmp_eq_u32_e64 s[10:11], 4, v1
	v_cmp_eq_u32_e64 s[12:13], 5, v1
	v_cmp_eq_u32_e64 s[14:15], 6, v1
	v_cmp_eq_u32_e64 s[16:17], 7, v1
	s_mov_b32 s29, 0xbfb8aa3b
	s_mov_b32 s46, 0x7f800000
	s_mov_b32 s47, 0x33800000
	s_movk_i32 s48, 0x2000
	s_mov_b64 s[38:39], 0x2800
	s_mov_b64 s[40:41], 0x800
	s_waitcnt vmcnt(14)
	v_pk_mul_f32 v[10:11], v[28:29], v[28:29]
	v_pk_mul_f32 v[12:13], v[26:27], v[26:27]
	s_waitcnt vmcnt(13)
	v_pk_mul_f32 v[14:15], v[20:21], v[20:21]
	v_pk_mul_f32 v[16:17], v[18:19], v[18:19]
	v_pk_mov_b32 v[84:85], v[12:13], v[10:11] op_sel:[1,0]
	v_mov_b32_e32 v13, v11
	v_pk_mov_b32 v[10:11], v[16:17], v[14:15] op_sel:[1,0]
	v_mov_b32_e32 v17, v15
	s_waitcnt vmcnt(11)
	v_mul_f32_e32 v66, v31, v31
	v_mul_f32_e32 v82, v33, v33
	v_pk_add_f32 v[12:13], v[84:85], v[12:13]
	v_pk_add_f32 v[10:11], v[10:11], v[16:17]
	v_mul_f32_e32 v89, v22, v22
	v_mul_f32_e32 v90, v23, v23
	v_mul_f32_e32 v91, v24, v24
	v_mul_f32_e32 v92, v25, v25
	v_pk_fma_f32 v[14:15], v[30:31], v[30:31], v[66:67] op_sel_hi:[1,1,0]
	v_pk_fma_f32 v[66:67], v[32:33], v[32:33], v[82:83] op_sel_hi:[1,1,0]
	v_pk_add_f32 v[12:13], v[12:13], v[12:13] op_sel:[0,1] op_sel_hi:[1,0]
	v_pk_add_f32 v[10:11], v[10:11], v[10:11] op_sel:[0,1] op_sel_hi:[1,0]
	v_mov_b32_e32 v15, v91
	v_mov_b32_e32 v67, v92
	v_mov_b32_e32 v13, v89
	v_mov_b32_e32 v11, v90
	v_pk_add_f32 v[14:15], v[14:15], v[66:67]
	v_pk_add_f32 v[10:11], v[12:13], v[10:11]
	v_cndmask_b32_e32 v82, v35, v83, vcc
	v_pk_add_f32 v[10:11], v[10:11], v[14:15]
	v_lshlrev_b32_e32 v166, 2, v82
	v_add_f32_e32 v66, v10, v11
	global_load_dwordx4 v[10:13], v54, s[8:9] offset:2064
	global_load_dwordx4 v[14:17], v54, s[8:9] offset:2048
	ds_bpermute_b32 v67, v165, v66
	s_waitcnt vmcnt(12)
	v_pk_add_f32 v[82:83], v[38:39], 1.0 op_sel_hi:[1,0]
	v_cmp_lt_i32_e32 vcc, v86, v87
	s_waitcnt vmcnt(11)
	v_pk_add_f32 v[44:45], v[44:45], 1.0 op_sel_hi:[1,0]
	s_waitcnt vmcnt(9)
	v_pk_add_f32 v[52:53], v[52:53], 1.0 op_sel_hi:[1,0]
	s_waitcnt lgkmcnt(0)
	v_add_f32_e32 v66, v66, v67
	ds_bpermute_b32 v67, v169, v66
	v_pk_add_f32 v[42:43], v[42:43], 1.0 op_sel_hi:[1,0]
	v_pk_add_f32 v[50:51], v[50:51], 1.0 op_sel_hi:[1,0]
	v_pk_add_f32 v[84:85], v[48:49], 1.0 op_sel_hi:[1,0]
	s_waitcnt vmcnt(5)
	v_pk_mul_f32 v[48:49], v[78:79], v[50:51]
	s_waitcnt lgkmcnt(0)
	v_add_f32_e32 v55, v66, v67
	ds_bpermute_b32 v66, v168, v55
	v_cndmask_b32_e32 v67, v35, v86, vcc
	v_lshlrev_b32_e32 v164, 2, v67
	v_pk_add_f32 v[86:87], v[46:47], 1.0 op_sel_hi:[1,0]
	v_pk_mul_f32 v[50:51], v[76:77], v[84:85]
	s_waitcnt lgkmcnt(0)
	v_add_f32_e32 v55, v55, v66
	ds_bpermute_b32 v73, v167, v55
	v_pk_add_f32 v[66:67], v[40:41], 1.0 op_sel_hi:[1,0]
	v_pk_mul_f32 v[40:41], v[62:63], v[42:43]
	v_pk_mul_f32 v[42:43], v[60:61], v[66:67]
	v_cmp_eq_u32_e64 s[8:9], 3, v1
	s_waitcnt lgkmcnt(0)
	v_add_f32_e32 v38, v55, v73
	ds_bpermute_b32 v39, v166, v38
	s_waitcnt lgkmcnt(0)
	v_add_f32_e32 v46, v38, v39
	ds_bpermute_b32 v47, v164, v46
	v_pk_mul_f32 v[38:39], v[64:65], v[44:45]
	v_pk_mul_f32 v[44:45], v[58:59], v[82:83]
	s_waitcnt lgkmcnt(0)
; #define GAS __attribute__((address_space(1)))
; #define LAS __attribute__((address_space(3)))
; __device__ __forceinline__ unsigned pk2(float lo, float hi) { return pg8::cvt_pk_bf16(lo, hi); }
; template <int LO, int HI> __global__ void __launch_bounds__(NWAVES * 64, 2) fox_fwd(Args args) {
;     ...
;             const float rstd = 1.0f / sqrtf(wave_sum(s2) * (1.0f / D) + EPS);
; #pragma unroll
;             for (int j = 0; j < 4; ++j) v[j] = v[j] * rstd * gm[j] + sh[j];
; #pragma unroll
;             for (int j = 0; j < 2; ++j) { v4u o; o.x = pk2(v[2 * j][0], v[2 * j][1]); o.y = pk2(v[2 * j][2], v[2 * j][3]); o.z = pk2(v[2 * j + 1][0], v[2 * j + 1][1]); o.w = pk2(v[2 * j + 1][2], v[2 * j + 1][3]);
;                 *(GAS v4u*)(HB + (size_t)m * D + 8 * lane + 512 * j) = o; }
;             float fl[8];
; #pragma unroll
;             for (int q = 0; q < 8; ++q) { float a = 0.f;
; #pragma unroll
;                 for (int j = 0; j < 4; ++j) { const f32x4 w = *(const LAS f32x4*)(wf + q * 1024 + P1COL(j)); a += (v[j][0] * w[0] + v[j][1] * w[1]) + (v[j][2] * w[2] + v[j][3] * w[3]); }
;                 fl[q] = wave_sum(a); }
	v_add_f32_e32 v46, v46, v47
	v_fmamk_f32 v46, v46, 0x3a800000, v69
	v_mul_f32_e32 v47, 0x4f800000, v46
	v_cmp_gt_f32_e32 vcc, s45, v46
	s_nop 1
	v_cndmask_b32_e32 v55, v46, v47, vcc
	v_sqrt_f32_e32 v58, v55
	v_pk_mul_f32 v[46:47], v[80:81], v[52:53]
	v_add_u32_e32 v52, -1, v58
	v_add_u32_e32 v53, 1, v58
	v_fma_f32 v59, -v52, v58, v55
	v_fma_f32 v60, -v53, v58, v55
	v_cmp_ge_f32_e64 s[4:5], 0, v59
	s_nop 1
	v_cndmask_b32_e64 v52, v58, v52, s[4:5]
	v_cmp_lt_f32_e64 s[4:5], 0, v60
	s_nop 1
	v_cndmask_b32_e64 v52, v52, v53, s[4:5]
	v_mul_f32_e32 v53, 0x37800000, v52
	v_cndmask_b32_e32 v52, v52, v53, vcc
	v_cmp_class_f32_e32 vcc, v55, v70
	s_nop 1
	v_cndmask_b32_e32 v55, v52, v55, vcc
	v_div_scale_f32 v58, s[4:5], v55, v55, 1.0
	v_rcp_f32_e32 v59, v58
	v_div_scale_f32 v60, vcc, 1.0, v55, 1.0
	v_pk_mul_f32 v[52:53], v[74:75], v[86:87]
	v_fma_f32 v61, -v58, v59, 1.0
	v_fmac_f32_e32 v59, v61, v59
	v_mul_f32_e32 v61, v60, v59
	v_fma_f32 v62, -v58, v61, v60
	v_fmac_f32_e32 v61, v62, v59
	v_fma_f32 v58, -v58, v61, v60
	v_div_fmas_f32 v58, v58, v59, v61
	v_div_fixup_f32 v64, v58, v55, 1.0
	v_pk_mul_f32 v[18:19], v[64:65], v[18:19] op_sel_hi:[0,1]
	v_pk_mul_f32 v[20:21], v[64:65], v[20:21] op_sel_hi:[0,1]
	s_waitcnt vmcnt(3)
	v_pk_fma_f32 v[60:61], v[42:43], v[20:21], v[4:5]
	v_pk_fma_f32 v[62:63], v[44:45], v[18:19], v[2:3]
	v_pk_mul_f32 v[18:19], v[64:65], v[30:31] op_sel_hi:[0,1]
	v_pk_mul_f32 v[20:21], v[64:65], v[32:33] op_sel_hi:[0,1]
	v_pk_mul_f32 v[58:59], v[64:65], v[26:27] op_sel_hi:[0,1]
	v_pk_mul_f32 v[26:27], v[64:65], v[28:29] op_sel_hi:[0,1]
	s_waitcnt vmcnt(0)
	v_pk_fma_f32 v[28:29], v[46:47], v[20:21], v[16:17]
	v_pk_fma_f32 v[30:31], v[48:49], v[18:19], v[14:15]
	v_pk_mul_f32 v[18:19], v[64:65], v[22:23] op_sel_hi:[0,1]
	v_pk_mul_f32 v[20:21], v[64:65], v[24:25] op_sel_hi:[0,1]
	v_pk_fma_f32 v[26:27], v[38:39], v[26:27], v[8:9]
	v_pk_fma_f32 v[58:59], v[40:41], v[58:59], v[6:7]
	v_pk_fma_f32 v[22:23], v[50:51], v[20:21], v[12:13]
	v_pk_fma_f32 v[24:25], v[52:53], v[18:19], v[10:11]
	v_lshl_add_u64 v[32:33], v[56:57], 0, s[34:35]
	v_cvt_pk_bf16_f32 v18, v58, v59
	v_cvt_pk_bf16_f32 v19, v26, v27
	v_cvt_pk_bf16_f32 v20, v62, v63
	v_cvt_pk_bf16_f32 v21, v60, v61
	global_store_dwordx4 v[32:33], v[18:21], off
	s_lshl_b64 s[4:5], s[36:37], 12
	s_add_u32 s4, s6, s4
	v_cvt_pk_bf16_f32 v18, v30, v31
	v_cvt_pk_bf16_f32 v19, v28, v29
	v_cvt_pk_bf16_f32 v20, v24, v25
	v_cvt_pk_bf16_f32 v21, v22, v23
	ds_read_b128 v[64:67], v72
	ds_read_b128 v[74:77], v72 offset:16
	global_store_dwordx4 v[32:33], v[18:21], off offset:1024
	ds_read_b128 v[18:21], v72 offset:12288
	s_addc_u32 s5, s7, s5
	s_waitcnt lgkmcnt(2)
	v_mul_f32_e32 v55, v59, v65
	v_fmac_f32_e32 v55, v58, v64
	v_mul_f32_e32 v64, v27, v67
	v_fmac_f32_e32 v64, v26, v66
	v_add_f32_e32 v55, v55, v64
	ds_read_b128 v[64:67], v72 offset:2048
	s_waitcnt lgkmcnt(2)
	v_mul_f32_e32 v73, v63, v75
	v_fmac_f32_e32 v73, v62, v74
	v_mul_f32_e32 v74, v61, v77
	v_fmac_f32_e32 v74, v60, v76
	v_add_f32_e32 v73, v73, v74
	ds_read_b128 v[74:77], v72 offset:2064
	s_waitcnt lgkmcnt(1)
	v_mul_f32_e32 v65, v31, v65
	v_fmac_f32_e32 v65, v30, v64
	v_mul_f32_e32 v64, v29, v67
	v_add_f32_e32 v55, 0, v55
	v_fmac_f32_e32 v64, v28, v66
	v_add_f32_e32 v55, v55, v73
	v_add_f32_e32 v64, v65, v64
	v_add_f32_e32 v55, v55, v64
	s_waitcnt lgkmcnt(0)
	v_mul_f32_e32 v64, v25, v75
	v_mul_f32_e32 v65, v23, v77
	v_fmac_f32_e32 v64, v24, v74
	v_fmac_f32_e32 v65, v22, v76
	v_add_f32_e32 v64, v64, v65
	v_add_f32_e32 v55, v55, v64
	ds_bpermute_b32 v64, v165, v55
	ds_read_b128 v[74:77], v72 offset:4112
	v_cmp_eq_u32_e64 s[6:7], 2, v1
	s_waitcnt lgkmcnt(1)
	v_add_f32_e32 v55, v55, v64
	ds_bpermute_b32 v64, v169, v55
	s_waitcnt lgkmcnt(1)
	v_mul_f32_e32 v75, v63, v75
	v_fmac_f32_e32 v75, v62, v74
	v_mul_f32_e32 v74, v61, v77
	v_fmac_f32_e32 v74, v60, v76
	s_waitcnt lgkmcnt(0)
	v_add_f32_e32 v55, v55, v64
	ds_read_b128 v[64:67], v72 offset:4096
	v_add_f32_e32 v74, v75, v74
	ds_bpermute_b32 v73, v168, v55
	s_waitcnt lgkmcnt(1)
	v_mul_f32_e32 v65, v59, v65
	v_fmac_f32_e32 v65, v58, v64
	v_mul_f32_e32 v64, v27, v67
	v_fmac_f32_e32 v64, v26, v66
	v_add_f32_e32 v64, v65, v64
	v_add_f32_e32 v78, 0, v64
	ds_read_b128 v[64:67], v72 offset:6144
	v_add_f32_e32 v78, v78, v74
	ds_read_b128 v[74:77], v72 offset:6160
	s_waitcnt lgkmcnt(2)
	v_add_f32_e32 v55, v55, v73
	ds_bpermute_b32 v73, v167, v55
	s_waitcnt lgkmcnt(2)
	v_mul_f32_e32 v65, v31, v65
	v_fmac_f32_e32 v65, v30, v64
	v_mul_f32_e32 v64, v29, v67
	v_fmac_f32_e32 v64, v28, v66
	v_add_f32_e32 v64, v65, v64
	s_waitcnt lgkmcnt(1)
	v_mul_f32_e32 v65, v25, v75
	v_mul_f32_e32 v66, v23, v77
	v_fmac_f32_e32 v65, v24, v74
	v_fmac_f32_e32 v66, v22, v76
	v_add_f32_e32 v64, v78, v64
	v_add_f32_e32 v65, v65, v66
	v_add_f32_e32 v64, v64, v65
	ds_bpermute_b32 v65, v165, v64
	s_waitcnt lgkmcnt(1)
	v_add_f32_e32 v55, v55, v73
	ds_bpermute_b32 v74, v166, v55
	v_lshlrev_b32_e32 v73, 3, v1
	s_waitcnt lgkmcnt(1)
	v_add_f32_e32 v75, v64, v65
	ds_bpermute_b32 v76, v169, v75
	ds_read_b128 v[64:67], v72 offset:8192
	s_waitcnt lgkmcnt(2)
	v_add_f32_e32 v55, v55, v74
	s_waitcnt lgkmcnt(1)
	v_add_f32_e32 v78, v75, v76
	ds_read_b128 v[74:77], v72 offset:8208
	s_waitcnt lgkmcnt(1)
	v_mul_f32_e32 v65, v59, v65
	v_fmac_f32_e32 v65, v58, v64
	v_mul_f32_e32 v64, v27, v67
	v_fmac_f32_e32 v64, v26, v66
	v_add_f32_e32 v64, v65, v64
	s_waitcnt lgkmcnt(0)
	v_mul_f32_e32 v75, v63, v75
	v_add_f32_e32 v80, 0, v64
	v_fmac_f32_e32 v75, v62, v74
	v_mul_f32_e32 v74, v61, v77
	ds_read_b128 v[64:67], v72 offset:10240
	v_fmac_f32_e32 v74, v60, v76
	v_add_f32_e32 v74, v75, v74
	v_add_f32_e32 v80, v80, v74
	ds_read_b128 v[74:77], v72 offset:10256
	s_waitcnt lgkmcnt(1)
; #define GAS __attribute__((address_space(1)))
; #define LAS __attribute__((address_space(3)))
; __device__ __forceinline__ unsigned pk2(float lo, float hi) { return pg8::cvt_pk_bf16(lo, hi); }
; template <int LO, int HI> __global__ void __launch_bounds__(NWAVES * 64, 2) fox_fwd(Args args) {
;     ...
;         for (int r = 0; r < 16; ++r) { const int m = m0 + r;
;             const GAS float* xr = (const GAS float*)(x + (size_t)m * D);
;             f32x4 v[4]; float s2 = 0.f;
; #pragma unroll
;             for (int j = 0; j < 4; ++j) { v[j] = *(const GAS f32x4*)(xr + P1COL(j)); s2 += (v[j][0] * v[j][0] + v[j][1] * v[j][1]) + (v[j][2] * v[j][2] + v[j][3] * v[j][3]); }
;             const float rstd = 1.0f / sqrtf(wave_sum(s2) * (1.0f / D) + EPS);
; #pragma unroll
;             for (int j = 0; j < 4; ++j) v[j] = v[j] * rstd * gm[j] + sh[j];
; #pragma unroll
;             for (int j = 0; j < 2; ++j) { v4u o; o.x = pk2(v[2 * j][0], v[2 * j][1]); o.y = pk2(v[2 * j][2], v[2 * j][3]); o.z = pk2(v[2 * j + 1][0], v[2 * j + 1][1]); o.w = pk2(v[2 * j + 1][2], v[2 * j + 1][3]);
;                 *(GAS v4u*)(HB + (size_t)m * D + 8 * lane + 512 * j) = o; }
;             float fl[8];
; #pragma unroll
;             for (int q = 0; q < 8; ++q) { float a = 0.f;
; #pragma unroll
;                 for (int j = 0; j < 4; ++j) { const f32x4 w = *(const LAS f32x4*)(wf + q * 1024 + P1COL(j)); a += (v[j][0] * w[0] + v[j][1] * w[1]) + (v[j][2] * w[2] + v[j][3] * w[3]); }
;                 fl[q] = wave_sum(a); }
	v_mul_f32_e32 v65, v31, v65
	ds_bpermute_b32 v79, v168, v78
	v_fmac_f32_e32 v65, v30, v64
	v_mul_f32_e32 v64, v29, v67
	v_fmac_f32_e32 v64, v28, v66
	v_add_f32_e32 v64, v65, v64
	s_waitcnt lgkmcnt(1)
	v_mul_f32_e32 v65, v25, v75
	v_mul_f32_e32 v66, v23, v77
	v_fmac_f32_e32 v65, v24, v74
	v_fmac_f32_e32 v66, v22, v76
	v_add_f32_e32 v64, v80, v64
	v_add_f32_e32 v65, v65, v66
	v_add_f32_e32 v64, v64, v65
	s_waitcnt lgkmcnt(0)
	v_add_f32_e32 v67, v78, v79
	ds_bpermute_b32 v65, v165, v64
	ds_bpermute_b32 v66, v164, v55
	ds_bpermute_b32 v74, v167, v67
	s_waitcnt lgkmcnt(2)
	v_add_f32_e32 v32, v64, v65
	s_waitcnt lgkmcnt(1)
	v_add_f32_e32 v55, v55, v66
	s_waitcnt lgkmcnt(0)
	v_add_f32_e32 v74, v67, v74
	ds_read_b128 v[64:67], v72 offset:12304
	v_mul_f32_e32 v19, v59, v19
	v_fmac_f32_e32 v19, v58, v18
	v_mul_f32_e32 v18, v27, v21
	v_fmac_f32_e32 v18, v26, v20
	v_add_f32_e32 v18, v19, v18
	s_waitcnt lgkmcnt(0)
	v_mul_f32_e32 v65, v63, v65
	v_add_f32_e32 v76, 0, v18
	v_fmac_f32_e32 v65, v62, v64
	v_mul_f32_e32 v64, v61, v67
	ds_read_b128 v[18:21], v72 offset:14336
	v_fmac_f32_e32 v64, v60, v66
	v_add_f32_e32 v64, v65, v64
	v_add_f32_e32 v76, v76, v64
	ds_read_b128 v[64:67], v72 offset:14352
	s_waitcnt lgkmcnt(1)
	v_mul_f32_e32 v19, v31, v19
	v_fmac_f32_e32 v19, v30, v18
	v_mul_f32_e32 v18, v29, v21
	v_fmac_f32_e32 v18, v28, v20
	v_add_f32_e32 v18, v19, v18
	s_waitcnt lgkmcnt(0)
	v_mul_f32_e32 v19, v25, v65
	v_mul_f32_e32 v20, v23, v67
	v_fmac_f32_e32 v19, v24, v64
	v_fmac_f32_e32 v20, v22, v66
	v_add_f32_e32 v18, v76, v18
	v_add_f32_e32 v19, v19, v20
	v_add_f32_e32 v64, v18, v19
	ds_bpermute_b32 v75, v166, v74
	ds_bpermute_b32 v65, v165, v64
	ds_read_b128 v[18:21], v72 offset:16384
	ds_bpermute_b32 v33, v169, v32
	s_waitcnt lgkmcnt(3)
	v_add_f32_e32 v74, v74, v75
	s_waitcnt lgkmcnt(2)
	v_add_f32_e32 v75, v64, v65
	ds_read_b128 v[64:67], v72 offset:16400
	s_waitcnt lgkmcnt(2)
	v_mul_f32_e32 v19, v59, v19
	v_fmac_f32_e32 v19, v58, v18
	v_mul_f32_e32 v18, v27, v21
	v_fmac_f32_e32 v18, v26, v20
	v_add_f32_e32 v18, v19, v18
	s_waitcnt lgkmcnt(0)
	v_mul_f32_e32 v65, v63, v65
	v_add_f32_e32 v77, 0, v18
	v_fmac_f32_e32 v65, v62, v64
	v_mul_f32_e32 v64, v61, v67
	ds_read_b128 v[18:21], v72 offset:18432
	v_fmac_f32_e32 v64, v60, v66
	v_add_f32_e32 v64, v65, v64
	v_add_f32_e32 v32, v32, v33
	v_add_f32_e32 v77, v77, v64
	ds_read_b128 v[64:67], v72 offset:18448
	ds_bpermute_b32 v33, v168, v32
	s_waitcnt lgkmcnt(2)
	v_mul_f32_e32 v19, v31, v19
	v_fmac_f32_e32 v19, v30, v18
	v_mul_f32_e32 v18, v29, v21
	v_fmac_f32_e32 v18, v28, v20
	v_add_f32_e32 v18, v19, v18
	s_waitcnt lgkmcnt(1)
	v_mul_f32_e32 v19, v25, v65
	v_mul_f32_e32 v20, v23, v67
	s_waitcnt lgkmcnt(0)
	v_add_f32_e32 v32, v32, v33
	ds_bpermute_b32 v76, v169, v75
	v_fmac_f32_e32 v19, v24, v64
	v_fmac_f32_e32 v20, v22, v66
	ds_bpermute_b32 v33, v167, v32
	v_add_f32_e32 v18, v77, v18
	v_add_f32_e32 v19, v19, v20
	v_add_f32_e32 v18, v18, v19
	ds_bpermute_b32 v19, v165, v18
	s_waitcnt lgkmcnt(2)
	v_add_f32_e32 v21, v75, v76
	s_waitcnt lgkmcnt(1)
	v_add_f32_e32 v20, v32, v33
	ds_bpermute_b32 v32, v168, v21
	ds_bpermute_b32 v33, v166, v20
	s_waitcnt lgkmcnt(2)
	v_add_f32_e32 v18, v18, v19
	ds_bpermute_b32 v19, v169, v18
	ds_bpermute_b32 v64, v164, v74
	s_waitcnt lgkmcnt(3)
	v_add_f32_e32 v21, v21, v32
	ds_bpermute_b32 v32, v167, v21
	s_waitcnt lgkmcnt(3)
	v_add_f32_e32 v20, v20, v33
	s_waitcnt lgkmcnt(2)
	v_add_f32_e32 v18, v18, v19
	ds_bpermute_b32 v19, v168, v18
	ds_bpermute_b32 v33, v164, v20
	s_waitcnt lgkmcnt(2)
	v_add_f32_e32 v21, v21, v32
	ds_bpermute_b32 v32, v166, v21
	v_add_f32_e32 v74, v74, v64
	s_waitcnt lgkmcnt(2)
	v_add_f32_e32 v64, v18, v19
	ds_bpermute_b32 v65, v167, v64
	s_waitcnt lgkmcnt(2)
	v_add_f32_e32 v75, v20, v33
	s_waitcnt lgkmcnt(1)
	v_add_f32_e32 v32, v21, v32
	ds_read_b128 v[18:21], v72 offset:20480
	ds_bpermute_b32 v33, v164, v32
	s_waitcnt lgkmcnt(2)
	v_add_f32_e32 v76, v64, v65
	ds_read_b128 v[64:67], v72 offset:20496
	ds_bpermute_b32 v77, v166, v76
	s_waitcnt lgkmcnt(3)
	v_mul_f32_e32 v19, v59, v19
	v_fmac_f32_e32 v19, v58, v18
	v_mul_f32_e32 v18, v27, v21
	v_fmac_f32_e32 v18, v26, v20
	v_add_f32_e32 v18, v19, v18
	s_waitcnt lgkmcnt(1)
	v_mul_f32_e32 v65, v63, v65
	v_add_f32_e32 v78, 0, v18
	v_fmac_f32_e32 v65, v62, v64
	v_mul_f32_e32 v64, v61, v67
	ds_read_b128 v[18:21], v72 offset:22528
	v_fmac_f32_e32 v64, v60, v66
	v_add_f32_e32 v64, v65, v64
	v_add_f32_e32 v78, v78, v64
	ds_read_b128 v[64:67], v72 offset:22544
	s_waitcnt lgkmcnt(1)
	v_mul_f32_e32 v19, v31, v19
	v_fmac_f32_e32 v19, v30, v18
	v_mul_f32_e32 v18, v29, v21
	v_fmac_f32_e32 v18, v28, v20
	v_add_f32_e32 v18, v19, v18
	s_waitcnt lgkmcnt(0)
	v_mul_f32_e32 v19, v25, v65
	v_mul_f32_e32 v20, v23, v67
	v_fmac_f32_e32 v19, v24, v64
	v_fmac_f32_e32 v20, v22, v66
	v_add_f32_e32 v18, v78, v18
	v_add_f32_e32 v19, v19, v20
	v_add_f32_e32 v64, v18, v19
	ds_bpermute_b32 v65, v165, v64
	ds_read_b128 v[18:21], v72 offset:24576
	v_add_f32_e32 v92, v32, v33
	v_add_f32_e32 v93, v76, v77
	ds_bpermute_b32 v94, v164, v93
	s_waitcnt lgkmcnt(2)
	v_add_f32_e32 v95, v64, v65
	ds_read_b128 v[64:67], v72 offset:24592
	s_waitcnt lgkmcnt(2)
	v_pk_mul_f32 v[18:19], v[58:59], v[18:19]
	v_pk_mul_f32 v[20:21], v[26:27], v[20:21]
	ds_bpermute_b32 v96, v169, v95
	v_pk_mov_b32 v[32:33], v[18:19], v[20:21] op_sel:[1,0]
	v_mov_b32_e32 v19, v21
	v_pk_add_f32 v[18:19], v[32:33], v[18:19]
	s_waitcnt lgkmcnt(1)
	v_pk_mul_f32 v[64:65], v[62:63], v[64:65]
	v_add_f32_e32 v18, v18, v19
	v_add_f32_e32 v32, 0, v18
	ds_read_b128 v[18:21], v72 offset:26624
	ds_read_b128 v[76:79], v72 offset:26640
	global_load_dwordx4 v[80:83], v54, s[4:5] offset:16
	global_load_dwordx4 v[84:87], v54, s[4:5]
	v_pk_mul_f32 v[66:67], v[60:61], v[66:67]
	s_waitcnt lgkmcnt(0)
; #define GAS __attribute__((address_space(1)))
; #define LAS __attribute__((address_space(3)))
; __device__ __forceinline__ unsigned pk2(float lo, float hi) { return pg8::cvt_pk_bf16(lo, hi); }
; template <int LO, int HI> __global__ void __launch_bounds__(NWAVES * 64, 2) fox_fwd(Args args) {
;     ...
;             f32x4 v[4]; float s2 = 0.f;
; #pragma unroll
;             for (int j = 0; j < 4; ++j) { v[j] = *(const GAS f32x4*)(xr + P1COL(j)); s2 += (v[j][0] * v[j][0] + v[j][1] * v[j][1]) + (v[j][2] * v[j][2] + v[j][3] * v[j][3]); }
;             const float rstd = 1.0f / sqrtf(wave_sum(s2) * (1.0f / D) + EPS);
; #pragma unroll
;             for (int j = 0; j < 4; ++j) v[j] = v[j] * rstd * gm[j] + sh[j];
; #pragma unroll
;             for (int j = 0; j < 2; ++j) { v4u o; o.x = pk2(v[2 * j][0], v[2 * j][1]); o.y = pk2(v[2 * j][2], v[2 * j][3]); o.z = pk2(v[2 * j + 1][0], v[2 * j + 1][1]); o.w = pk2(v[2 * j + 1][2], v[2 * j + 1][3]);
;                 *(GAS v4u*)(HB + (size_t)m * D + 8 * lane + 512 * j) = o; }
;             float fl[8];
; #pragma unroll
;             for (int q = 0; q < 8; ++q) { float a = 0.f;
; #pragma unroll
;                 for (int j = 0; j < 4; ++j) { const f32x4 w = *(const LAS f32x4*)(wf + q * 1024 + P1COL(j)); a += (v[j][0] * w[0] + v[j][1] * w[1]) + (v[j][2] * w[2] + v[j][3] * w[3]); }
;                 fl[q] = wave_sum(a); }
;             float mine = fl[0];
; #pragma unroll
;             for (int q = 1; q < 8; ++q) mine = (lane == q) ? fl[q] : mine;
;             { const float z = mine + bfv; const float ls = fminf(z, 0.f) - log1pf(__expf(-fabsf(z)));
	v_mul_f32_e32 v33, v24, v76
	v_pk_mov_b32 v[88:89], v[64:65], v[66:67] op_sel:[1,0]
	v_mov_b32_e32 v65, v67
	v_pk_add_f32 v[64:65], v[88:89], v[64:65]
	v_mul_f32_e32 v66, v25, v77
	v_mul_f32_e32 v67, v22, v78
	v_mul_f32_e32 v97, v23, v79
	global_load_dwordx4 v[76:79], v54, s[4:5] offset:2048
	global_load_dwordx4 v[88:91], v54, s[4:5] offset:2064
	v_pk_add_f32 v[64:65], v[64:65], v[64:65] op_sel:[0,1] op_sel_hi:[1,0]
	v_cmp_eq_u32_e64 s[4:5], 1, v1
	v_mov_b32_e32 v65, v66
	v_pk_add_f32 v[32:33], v[32:33], v[64:65]
	v_mul_f32_e32 v64, v31, v19
	v_pk_fma_f32 v[18:19], v[30:31], v[18:19], v[64:65] op_sel_hi:[1,1,0]
	v_mul_f32_e32 v64, v29, v21
	v_pk_fma_f32 v[20:21], v[28:29], v[20:21], v[64:65] op_sel_hi:[1,1,0]
	v_mov_b32_e32 v19, v67
	v_mov_b32_e32 v21, v97
	v_pk_add_f32 v[64:65], v[18:19], v[20:21]
	ds_read_b128 v[18:21], v72 offset:28672
	v_pk_add_f32 v[32:33], v[32:33], v[64:65]
	ds_read_b128 v[64:67], v72 offset:28688
	v_add_f32_e32 v97, v32, v33
	ds_bpermute_b32 v98, v165, v97
	s_waitcnt lgkmcnt(2)
	v_pk_mul_f32 v[18:19], v[58:59], v[18:19]
	v_pk_mul_f32 v[20:21], v[26:27], v[20:21]
	s_waitcnt lgkmcnt(1)
	v_pk_mul_f32 v[32:33], v[62:63], v[64:65]
	v_pk_mov_b32 v[26:27], v[18:19], v[20:21] op_sel:[1,0]
	v_mov_b32_e32 v19, v21
	v_pk_add_f32 v[18:19], v[26:27], v[18:19]
	v_pk_mul_f32 v[58:59], v[60:61], v[66:67]
	v_add_f32_e32 v18, v18, v19
	v_add_f32_e32 v26, 0, v18
	ds_read_b128 v[18:21], v72 offset:30720
	ds_read_b128 v[62:65], v72 offset:30736
	v_pk_mov_b32 v[60:61], v[32:33], v[58:59] op_sel:[1,0]
	v_mov_b32_e32 v33, v59
	v_pk_add_f32 v[32:33], v[60:61], v[32:33]
	s_waitcnt lgkmcnt(0)
	v_mul_f32_e32 v27, v24, v62
	v_mul_f32_e32 v24, v25, v63
	v_mul_f32_e32 v25, v22, v64
	v_mul_f32_e32 v58, v23, v65
	v_pk_add_f32 v[22:23], v[32:33], v[32:33] op_sel:[0,1] op_sel_hi:[1,0]
	s_nop 0
	v_mov_b32_e32 v23, v24
	v_mul_f32_e32 v24, v31, v19
	v_pk_fma_f32 v[18:19], v[30:31], v[18:19], v[24:25] op_sel_hi:[1,1,0]
	v_mul_f32_e32 v24, v29, v21
	v_pk_fma_f32 v[20:21], v[28:29], v[20:21], v[24:25] op_sel_hi:[1,1,0]
	v_mov_b32_e32 v19, v25
	v_mov_b32_e32 v21, v58
	v_pk_add_f32 v[22:23], v[26:27], v[22:23]
	v_pk_add_f32 v[18:19], v[18:19], v[20:21]
	v_add_f32_e32 v20, v95, v96
	v_pk_add_f32 v[18:19], v[22:23], v[18:19]
	ds_bpermute_b32 v21, v168, v20
	v_add_f32_e32 v18, v18, v19
	ds_bpermute_b32 v19, v165, v18
	v_add_f32_e32 v22, v97, v98
	ds_bpermute_b32 v23, v169, v22
	s_waitcnt lgkmcnt(2)
	v_add_f32_e32 v20, v20, v21
	ds_bpermute_b32 v21, v167, v20
	s_waitcnt lgkmcnt(2)
	v_add_f32_e32 v18, v18, v19
	ds_bpermute_b32 v19, v169, v18
	s_waitcnt lgkmcnt(2)
	v_add_f32_e32 v22, v22, v23
	ds_bpermute_b32 v23, v168, v22
	s_waitcnt lgkmcnt(2)
	v_add_f32_e32 v20, v20, v21
	ds_bpermute_b32 v21, v166, v20
	s_waitcnt lgkmcnt(2)
	v_add_f32_e32 v18, v18, v19
	ds_bpermute_b32 v19, v168, v18
	s_waitcnt lgkmcnt(2)
	v_add_f32_e32 v22, v22, v23
	ds_bpermute_b32 v23, v167, v22
	s_waitcnt lgkmcnt(2)
	v_add_f32_e32 v26, v20, v21
	ds_bpermute_b32 v27, v164, v26
	s_waitcnt lgkmcnt(2)
	v_add_f32_e32 v18, v18, v19
	ds_bpermute_b32 v19, v167, v18
	s_waitcnt vmcnt(2)
	v_pk_mul_f32 v[20:21], v[84:85], v[84:85]
	s_waitcnt lgkmcnt(2)
	v_add_f32_e32 v28, v22, v23
	ds_bpermute_b32 v29, v166, v28
	s_waitcnt lgkmcnt(1)
	v_add_f32_e32 v30, v18, v19
	v_pk_mul_f32 v[18:19], v[86:87], v[86:87]
	ds_bpermute_b32 v31, v166, v30
	v_pk_mov_b32 v[22:23], v[20:21], v[18:19] op_sel:[1,0]
	v_mov_b32_e32 v21, v19
	v_pk_add_f32 v[18:19], v[22:23], v[20:21]
	v_pk_mul_f32 v[20:21], v[82:83], v[82:83]
	v_pk_mul_f32 v[22:23], v[80:81], v[80:81]
	v_pk_add_f32 v[18:19], v[18:19], v[18:19] op_sel:[0,1] op_sel_hi:[1,0]
	v_pk_mov_b32 v[24:25], v[22:23], v[20:21] op_sel:[1,0]
	v_mov_b32_e32 v23, v21
	v_pk_add_f32 v[20:21], v[24:25], v[22:23]
	s_waitcnt vmcnt(0)
	v_mul_f32_e32 v22, v88, v88
	v_mul_f32_e32 v23, v89, v89
	v_pk_add_f32 v[20:21], v[20:21], v[20:21] op_sel:[0,1] op_sel_hi:[1,0]
	v_mov_b32_e32 v19, v22
	v_mov_b32_e32 v21, v23
	v_pk_add_f32 v[18:19], v[18:19], v[20:21]
	v_mul_f32_e32 v20, v77, v77
	v_mul_f32_e32 v22, v79, v79
	v_mul_f32_e32 v24, v90, v90
	v_mul_f32_e32 v25, v91, v91
	v_pk_fma_f32 v[20:21], v[76:77], v[76:77], v[20:21] op_sel_hi:[1,1,0]
	v_pk_fma_f32 v[22:23], v[78:79], v[78:79], v[22:23] op_sel_hi:[1,1,0]
	v_mov_b32_e32 v21, v24
	v_mov_b32_e32 v23, v25
	v_pk_add_f32 v[20:21], v[20:21], v[22:23]
	s_waitcnt lgkmcnt(0)
	v_add_f32_e32 v22, v30, v31
	v_pk_add_f32 v[18:19], v[18:19], v[20:21]
	v_add_f32_e32 v20, v28, v29
	v_add_f32_e32 v18, v18, v19
	ds_bpermute_b32 v19, v165, v18
	ds_bpermute_b32 v21, v164, v20
	ds_bpermute_b32 v23, v164, v22
	v_add_f32_e32 v24, v93, v94
	v_add_f32_e32 v25, v26, v27
	s_waitcnt lgkmcnt(2)
	v_add_f32_e32 v18, v18, v19
	ds_bpermute_b32 v19, v169, v18
	s_waitcnt lgkmcnt(2)
	v_add_f32_e32 v20, v20, v21
	s_waitcnt lgkmcnt(1)
	v_add_f32_e32 v21, v22, v23
	v_cndmask_b32_e64 v22, v55, v74, s[4:5]
	v_cndmask_b32_e64 v22, v22, v75, s[6:7]
	s_waitcnt lgkmcnt(0)
	v_add_f32_e32 v18, v18, v19
	ds_bpermute_b32 v19, v168, v18
	v_cndmask_b32_e64 v22, v22, v92, s[8:9]
	v_cndmask_b32_e64 v22, v22, v24, s[10:11]
	v_cndmask_b32_e64 v22, v22, v25, s[12:13]
	v_cndmask_b32_e64 v20, v22, v20, s[14:15]
	s_waitcnt lgkmcnt(0)
	v_add_f32_e32 v18, v18, v19
	ds_bpermute_b32 v19, v167, v18
	v_cndmask_b32_e64 v20, v20, v21, s[16:17]
	v_add_f32_e32 v20, v71, v20
	v_min_f32_e32 v22, 0, v20
	v_mul_f32_e64 v20, |v20|, s29
	s_waitcnt lgkmcnt(0)
	v_add_f32_e32 v18, v18, v19
	ds_bpermute_b32 v19, v166, v18
	v_exp_f32_e32 v55, v20
	s_waitcnt lgkmcnt(0)
	v_add_f32_e32 v18, v18, v19
	ds_bpermute_b32 v19, v164, v18
	v_add_f32_e32 v92, 1.0, v55
	v_add_f32_e32 v23, -1.0, v92
	v_sub_f32_e32 v26, v23, v92
	v_add_f32_e32 v26, 1.0, v26
	s_waitcnt lgkmcnt(0)
; #define GAS __attribute__((address_space(1)))
; #define LAS __attribute__((address_space(3)))
; __device__ __forceinline__ unsigned pk2(float lo, float hi) { return pg8::cvt_pk_bf16(lo, hi); }
; template <int LO, int HI> __global__ void __launch_bounds__(NWAVES * 64, 2) fox_fwd(Args args) {
;     ...
;             const float rstd = 1.0f / sqrtf(wave_sum(s2) * (1.0f / D) + EPS);
; #pragma unroll
;             for (int j = 0; j < 4; ++j) v[j] = v[j] * rstd * gm[j] + sh[j];
; #pragma unroll
;             for (int j = 0; j < 2; ++j) { v4u o; o.x = pk2(v[2 * j][0], v[2 * j][1]); o.y = pk2(v[2 * j][2], v[2 * j][3]); o.z = pk2(v[2 * j + 1][0], v[2 * j + 1][1]); o.w = pk2(v[2 * j + 1][2], v[2 * j + 1][3]);
;                 *(GAS v4u*)(HB + (size_t)m * D + 8 * lane + 512 * j) = o; }
;             float fl[8];
; #pragma unroll
;             for (int q = 0; q < 8; ++q) { float a = 0.f;
; #pragma unroll
;                 for (int j = 0; j < 4; ++j) { const f32x4 w = *(const LAS f32x4*)(wf + q * 1024 + P1COL(j)); a += (v[j][0] * w[0] + v[j][1] * w[1]) + (v[j][2] * w[2] + v[j][3] * w[3]); }
;                 fl[q] = wave_sum(a); }
	v_add_f32_e32 v18, v18, v19
	v_fmamk_f32 v18, v18, 0x3a800000, v69
	v_mul_f32_e32 v19, 0x4f800000, v18
	v_cmp_gt_f32_e32 vcc, s45, v18
	v_sub_f32_e32 v23, v55, v23
	v_add_f32_e32 v23, v23, v26
	v_cndmask_b32_e32 v18, v18, v19, vcc
	v_sqrt_f32_e32 v19, v18
	s_nop 0
	v_add_u32_e32 v20, -1, v19
	v_fma_f32 v21, -v20, v19, v18
	v_cmp_ge_f32_e64 s[20:21], 0, v21
	v_add_u32_e32 v21, 1, v19
	s_nop 0
	v_cndmask_b32_e64 v20, v19, v20, s[20:21]
	v_fma_f32 v19, -v21, v19, v18
	v_cmp_lt_f32_e64 s[20:21], 0, v19
	s_nop 1
	v_cndmask_b32_e64 v19, v20, v21, s[20:21]
	v_mul_f32_e32 v20, 0x37800000, v19
	v_cndmask_b32_e32 v19, v19, v20, vcc
	v_cmp_class_f32_e32 vcc, v18, v70
	s_nop 1
	v_cndmask_b32_e32 v18, v19, v18, vcc
	v_div_scale_f32 v19, s[20:21], v18, v18, 1.0
	v_rcp_f32_e32 v20, v19
	s_lshl_b64 s[20:21], s[36:37], 11
	s_mov_b32 s37, 0x3f2aaaab
	s_mov_b32 s36, 0x3f317218
	v_fma_f32 v21, -v19, v20, 1.0
	v_fmac_f32_e32 v20, v21, v20
	v_div_scale_f32 v21, vcc, 1.0, v18, 1.0
	v_mul_f32_e32 v24, v21, v20
	v_fma_f32 v25, -v19, v24, v21
	v_fmac_f32_e32 v24, v25, v20
	v_fma_f32 v19, -v19, v24, v21
	v_div_fmas_f32 v19, v19, v20, v24
	v_div_fixup_f32 v18, v19, v18, 1.0
	v_pk_mul_f32 v[20:21], v[18:19], v[84:85] op_sel_hi:[0,1]
	v_pk_mul_f32 v[24:25], v[18:19], v[86:87] op_sel_hi:[0,1]
	v_pk_fma_f32 v[64:65], v[40:41], v[20:21], v[6:7]
	v_pk_mul_f32 v[20:21], v[18:19], v[80:81] op_sel_hi:[0,1]
	v_pk_fma_f32 v[62:63], v[38:39], v[24:25], v[8:9]
	v_pk_mul_f32 v[24:25], v[18:19], v[82:83] op_sel_hi:[0,1]
	v_pk_fma_f32 v[66:67], v[44:45], v[20:21], v[2:3]
	v_pk_mul_f32 v[20:21], v[18:19], v[76:77] op_sel_hi:[0,1]
	v_pk_fma_f32 v[32:33], v[42:43], v[24:25], v[4:5]
	v_pk_mul_f32 v[24:25], v[18:19], v[78:79] op_sel_hi:[0,1]
	v_pk_fma_f32 v[30:31], v[48:49], v[20:21], v[14:15]
	v_pk_mul_f32 v[20:21], v[18:19], v[88:89] op_sel_hi:[0,1]
	v_pk_mul_f32 v[18:19], v[18:19], v[90:91] op_sel_hi:[0,1]
	v_pk_fma_f32 v[28:29], v[46:47], v[24:25], v[16:17]
	v_pk_fma_f32 v[58:59], v[50:51], v[18:19], v[12:13]
	v_pk_fma_f32 v[60:61], v[52:53], v[20:21], v[10:11]
	v_lshl_add_u64 v[24:25], v[56:57], 0, s[20:21]
	v_cvt_pk_bf16_f32 v18, v64, v65
	v_cvt_pk_bf16_f32 v19, v62, v63
	v_cvt_pk_bf16_f32 v20, v66, v67
	v_cvt_pk_bf16_f32 v21, v32, v33
	global_store_dwordx4 v[24:25], v[18:21], off
	s_mov_b32 s20, 0x3e9b6dac
	s_nop 0
	v_cvt_pk_bf16_f32 v18, v30, v31
	v_cvt_pk_bf16_f32 v19, v28, v29
	v_cvt_pk_bf16_f32 v20, v60, v61
	v_cvt_pk_bf16_f32 v21, v58, v59
	ds_read_b128 v[74:77], v72
	ds_read_b128 v[78:81], v72 offset:16
	s_waitcnt lgkmcnt(1)
	v_mul_f32_e32 v26, v65, v75
	v_mul_f32_e32 v27, v63, v77
	v_fmac_f32_e32 v26, v64, v74
	v_fmac_f32_e32 v27, v62, v76
	ds_read_b128 v[74:77], v72 offset:2048
	v_add_f32_e32 v26, v26, v27
	s_waitcnt lgkmcnt(1)
	v_mul_f32_e32 v27, v67, v79
	v_mul_f32_e32 v56, v33, v81
	v_fmac_f32_e32 v27, v66, v78
	v_fmac_f32_e32 v56, v32, v80
	ds_read_b128 v[78:81], v72 offset:2064
	v_add_f32_e32 v26, 0, v26
	v_add_f32_e32 v27, v27, v56
	v_add_f32_e32 v26, v26, v27
	s_waitcnt lgkmcnt(1)
	v_mul_f32_e32 v27, v31, v75
	v_mul_f32_e32 v56, v29, v77
	v_fmac_f32_e32 v27, v30, v74
	v_fmac_f32_e32 v56, v28, v76
	v_add_f32_e32 v27, v27, v56
	v_add_f32_e32 v26, v26, v27
	s_waitcnt lgkmcnt(0)
	v_mul_f32_e32 v27, v61, v79
	v_mul_f32_e32 v56, v59, v81
	v_fmac_f32_e32 v27, v60, v78
	v_fmac_f32_e32 v56, v58, v80
	v_add_f32_e32 v27, v27, v56
	v_add_f32_e32 v56, v26, v27
	ds_bpermute_b32 v57, v165, v56
	v_frexp_mant_f32_e32 v74, v92
	v_cmp_gt_f32_e32 vcc, s37, v74
	ds_read_b128 v[74:77], v72 offset:4096
	v_cvt_f64_f32_e32 v[26:27], v92
	s_waitcnt lgkmcnt(1)
	v_add_f32_e32 v57, v56, v57
	ds_bpermute_b32 v78, v169, v57
	v_frexp_exp_i32_f64_e32 v26, v[26:27]
	v_subbrev_co_u32_e32 v56, vcc, 0, v26, vcc
	v_sub_u32_e32 v27, 0, v56
	s_waitcnt lgkmcnt(0)
	v_add_f32_e32 v57, v57, v78
	ds_read_b128 v[78:81], v72 offset:4112
	v_mul_f32_e32 v26, v65, v75
	v_fmac_f32_e32 v26, v64, v74
	v_mul_f32_e32 v74, v63, v77
	v_fmac_f32_e32 v74, v62, v76
	v_add_f32_e32 v26, v26, v74
	s_waitcnt lgkmcnt(0)
	v_mul_f32_e32 v79, v67, v79
	ds_read_b128 v[74:77], v72 offset:6144
	v_fmac_f32_e32 v79, v66, v78
	v_mul_f32_e32 v78, v33, v81
	v_fmac_f32_e32 v78, v32, v80
	v_add_f32_e32 v26, 0, v26
	v_add_f32_e32 v78, v79, v78
	v_add_f32_e32 v26, v26, v78
	ds_read_b128 v[78:81], v72 offset:6160
	s_waitcnt lgkmcnt(1)
	v_mul_f32_e32 v75, v31, v75
	v_fmac_f32_e32 v75, v30, v74
	v_mul_f32_e32 v74, v29, v77
	v_fmac_f32_e32 v74, v28, v76
	v_add_f32_e32 v74, v75, v74
	v_add_f32_e32 v26, v26, v74
	s_waitcnt lgkmcnt(0)
	v_mul_f32_e32 v74, v61, v79
	v_mul_f32_e32 v75, v59, v81
	v_fmac_f32_e32 v74, v60, v78
	v_fmac_f32_e32 v75, v58, v80
	v_add_f32_e32 v74, v74, v75
	v_add_f32_e32 v78, v26, v74
	ds_bpermute_b32 v79, v165, v78
	ds_read_b128 v[74:77], v72 offset:8192
	ds_bpermute_b32 v82, v168, v57
	v_ldexp_f32 v26, v92, v27
	s_waitcnt lgkmcnt(2)
	v_add_f32_e32 v83, v78, v79
	ds_read_b128 v[78:81], v72 offset:8208
	s_waitcnt lgkmcnt(2)
	v_mul_f32_e32 v75, v65, v75
	v_fmac_f32_e32 v75, v64, v74
	v_mul_f32_e32 v74, v63, v77
	v_fmac_f32_e32 v74, v62, v76
	v_add_f32_e32 v74, v75, v74
	s_waitcnt lgkmcnt(0)
	v_mul_f32_e32 v79, v67, v79
	v_add_f32_e32 v85, 0, v74
	v_fmac_f32_e32 v79, v66, v78
	v_mul_f32_e32 v78, v33, v81
	ds_read_b128 v[74:77], v72 offset:10240
	v_fmac_f32_e32 v78, v32, v80
	v_add_f32_e32 v78, v79, v78
	v_add_f32_e32 v85, v85, v78
	ds_read_b128 v[78:81], v72 offset:10256
	s_waitcnt lgkmcnt(1)
	v_mul_f32_e32 v75, v31, v75
	v_fmac_f32_e32 v75, v30, v74
	v_mul_f32_e32 v74, v29, v77
	v_fmac_f32_e32 v74, v28, v76
	v_add_f32_e32 v57, v57, v82
	v_add_f32_e32 v74, v75, v74
	s_waitcnt lgkmcnt(0)
; #define LAS __attribute__((address_space(3)))
; template <int LO, int HI> __global__ void __launch_bounds__(NWAVES * 64, 2) fox_fwd(Args args) {
;     ...
;             for (int q = 0; q < 8; ++q) { float a = 0.f;
; #pragma unroll
;                 for (int j = 0; j < 4; ++j) { const f32x4 w = *(const LAS f32x4*)(wf + q * 1024 + P1COL(j)); a += (v[j][0] * w[0] + v[j][1] * w[1]) + (v[j][2] * w[2] + v[j][3] * w[3]); }
;                 fl[q] = wave_sum(a); }
	v_mul_f32_e32 v75, v61, v79
	v_mul_f32_e32 v76, v59, v81
	ds_bpermute_b32 v82, v167, v57
	v_fmac_f32_e32 v75, v60, v78
	v_fmac_f32_e32 v76, v58, v80
	v_add_f32_e32 v74, v85, v74
	v_add_f32_e32 v75, v75, v76
	v_add_f32_e32 v74, v74, v75
	ds_bpermute_b32 v84, v169, v83
	ds_bpermute_b32 v75, v165, v74
	s_waitcnt lgkmcnt(2)
	v_add_f32_e32 v57, v57, v82
	ds_bpermute_b32 v76, v166, v57
	s_waitcnt lgkmcnt(2)
	v_add_f32_e32 v77, v83, v84
	s_waitcnt lgkmcnt(1)
	v_add_f32_e32 v74, v74, v75
	ds_bpermute_b32 v78, v168, v77
	ds_bpermute_b32 v75, v169, v74
	s_waitcnt lgkmcnt(2)
	v_add_f32_e32 v57, v57, v76
	ds_bpermute_b32 v76, v164, v57
	s_waitcnt lgkmcnt(2)
	v_add_f32_e32 v78, v77, v78
	s_waitcnt lgkmcnt(1)
	v_add_f32_e32 v80, v74, v75
	ds_bpermute_b32 v79, v167, v78
	ds_bpermute_b32 v81, v168, v80
	s_waitcnt lgkmcnt(2)
	v_add_f32_e32 v57, v57, v76
	ds_read_b128 v[74:77], v72 offset:12288
	s_waitcnt lgkmcnt(2)
	v_add_f32_e32 v82, v78, v79
	s_waitcnt lgkmcnt(1)
	v_add_f32_e32 v84, v80, v81
	ds_read_b128 v[78:81], v72 offset:12304
	s_waitcnt lgkmcnt(1)
	v_mul_f32_e32 v75, v65, v75
	v_fmac_f32_e32 v75, v64, v74
	v_mul_f32_e32 v74, v63, v77
	v_fmac_f32_e32 v74, v62, v76
	v_add_f32_e32 v74, v75, v74
	s_waitcnt lgkmcnt(0)
	v_mul_f32_e32 v79, v67, v79
	v_add_f32_e32 v85, 0, v74
	v_fmac_f32_e32 v79, v66, v78
	v_mul_f32_e32 v78, v33, v81
	ds_read_b128 v[74:77], v72 offset:14336
	v_fmac_f32_e32 v78, v32, v80
	v_add_f32_e32 v78, v79, v78
	v_add_f32_e32 v85, v85, v78
	ds_read_b128 v[78:81], v72 offset:14352
	s_waitcnt lgkmcnt(1)
	v_mul_f32_e32 v75, v31, v75
	v_fmac_f32_e32 v75, v30, v74
	v_mul_f32_e32 v74, v29, v77
	v_fmac_f32_e32 v74, v28, v76
	v_add_f32_e32 v74, v75, v74
	s_waitcnt lgkmcnt(0)
	v_mul_f32_e32 v79, v61, v79
	v_add_f32_e32 v85, v85, v74
	v_fmac_f32_e32 v79, v60, v78
	v_mul_f32_e32 v78, v59, v81
	ds_read_b128 v[74:77], v72 offset:16384
	v_fmac_f32_e32 v78, v58, v80
	v_add_f32_e32 v78, v79, v78
	v_add_f32_e32 v85, v85, v78
	ds_read_b128 v[78:81], v72 offset:16400
	s_waitcnt lgkmcnt(1)
	v_mul_f32_e32 v75, v65, v75
	v_fmac_f32_e32 v75, v64, v74
	v_mul_f32_e32 v74, v63, v77
	v_fmac_f32_e32 v74, v62, v76
	v_add_f32_e32 v74, v75, v74
	s_waitcnt lgkmcnt(0)
	v_mul_f32_e32 v79, v67, v79
	v_add_f32_e32 v87, 0, v74
	v_fmac_f32_e32 v79, v66, v78
	v_mul_f32_e32 v78, v33, v81
	ds_read_b128 v[74:77], v72 offset:18432
	v_fmac_f32_e32 v78, v32, v80
	v_add_f32_e32 v78, v79, v78
	v_add_f32_e32 v87, v87, v78
	ds_read_b128 v[78:81], v72 offset:18448
	s_waitcnt lgkmcnt(1)
	v_mul_f32_e32 v75, v31, v75
	v_fmac_f32_e32 v75, v30, v74
	v_mul_f32_e32 v74, v29, v77
	v_fmac_f32_e32 v74, v28, v76
	v_add_f32_e32 v74, v75, v74
	s_waitcnt lgkmcnt(0)
	v_mul_f32_e32 v75, v61, v79
	v_mul_f32_e32 v76, v59, v81
	v_fmac_f32_e32 v75, v60, v78
	v_fmac_f32_e32 v76, v58, v80
	v_add_f32_e32 v74, v87, v74
	v_add_f32_e32 v75, v75, v76
	v_add_f32_e32 v74, v74, v75
	ds_bpermute_b32 v86, v165, v85
	ds_bpermute_b32 v75, v165, v74
	ds_bpermute_b32 v76, v167, v84
	ds_bpermute_b32 v83, v166, v82
	s_waitcnt lgkmcnt(3)
	v_add_f32_e32 v77, v85, v86
	s_waitcnt lgkmcnt(2)
	v_add_f32_e32 v74, v74, v75
	ds_bpermute_b32 v78, v169, v77
	ds_bpermute_b32 v75, v169, v74
	s_waitcnt lgkmcnt(3)
	v_add_f32_e32 v76, v84, v76
	ds_bpermute_b32 v80, v166, v76
	s_waitcnt lgkmcnt(3)
	v_add_f32_e32 v79, v82, v83
	s_waitcnt lgkmcnt(2)
	v_add_f32_e32 v77, v77, v78
	s_waitcnt lgkmcnt(1)
	v_add_f32_e32 v74, v74, v75
	ds_bpermute_b32 v78, v168, v77
	ds_bpermute_b32 v75, v168, v74
	ds_bpermute_b32 v81, v164, v79
	s_waitcnt lgkmcnt(3)
	v_add_f32_e32 v76, v76, v80
	ds_bpermute_b32 v82, v164, v76
	s_waitcnt lgkmcnt(3)
	v_add_f32_e32 v77, v77, v78
	s_waitcnt lgkmcnt(2)
	v_add_f32_e32 v75, v74, v75
	ds_bpermute_b32 v78, v167, v77
	ds_bpermute_b32 v80, v167, v75
	s_waitcnt lgkmcnt(3)
	v_add_f32_e32 v74, v79, v81
	s_waitcnt lgkmcnt(1)
	v_add_f32_e32 v77, v77, v78
	s_waitcnt lgkmcnt(0)
	v_add_f32_e32 v79, v75, v80
	ds_bpermute_b32 v78, v166, v77
	ds_bpermute_b32 v84, v166, v79
	v_add_f32_e32 v75, v76, v82
	ds_read_b128 v[80:83], v72 offset:20480
	s_waitcnt lgkmcnt(2)
	v_add_f32_e32 v76, v77, v78
	s_waitcnt lgkmcnt(1)
	v_add_f32_e32 v78, v79, v84
	ds_read_b128 v[84:87], v72 offset:20496
	s_waitcnt lgkmcnt(1)
	v_mul_f32_e32 v81, v65, v81
	v_fmac_f32_e32 v81, v64, v80
	v_mul_f32_e32 v80, v63, v83
	v_fmac_f32_e32 v80, v62, v82
	v_add_f32_e32 v80, v81, v80
	s_waitcnt lgkmcnt(0)
	v_mul_f32_e32 v85, v67, v85
	v_add_f32_e32 v88, 0, v80
	v_fmac_f32_e32 v85, v66, v84
	v_mul_f32_e32 v84, v33, v87
	ds_read_b128 v[80:83], v72 offset:22528
	v_fmac_f32_e32 v84, v32, v86
	v_add_f32_e32 v84, v85, v84
	v_add_f32_e32 v88, v88, v84
	ds_read_b128 v[84:87], v72 offset:22544
	s_waitcnt lgkmcnt(1)
	v_mul_f32_e32 v81, v31, v81
	v_fmac_f32_e32 v81, v30, v80
	v_mul_f32_e32 v80, v29, v83
	v_fmac_f32_e32 v80, v28, v82
	v_add_f32_e32 v80, v81, v80
	s_waitcnt lgkmcnt(0)
	v_mul_f32_e32 v81, v61, v85
	v_fmac_f32_e32 v81, v60, v84
	ds_read_b128 v[82:85], v72 offset:24576
	v_mul_f32_e32 v87, v59, v87
	v_fmac_f32_e32 v87, v58, v86
	v_add_f32_e32 v80, v88, v80
	v_add_f32_e32 v81, v81, v87
	ds_read_b128 v[86:89], v72 offset:24592
	s_waitcnt lgkmcnt(1)
	v_pk_mul_f32 v[82:83], v[64:65], v[82:83]
	v_pk_mul_f32 v[84:85], v[62:63], v[84:85]
	v_add_f32_e32 v80, v80, v81
	v_pk_mov_b32 v[90:91], v[82:83], v[84:85] op_sel:[1,0]
	v_mov_b32_e32 v83, v85
	v_pk_add_f32 v[82:83], v[90:91], v[82:83]
	s_waitcnt lgkmcnt(0)
	v_pk_mul_f32 v[86:87], v[66:67], v[86:87]
	v_add_f32_e32 v82, v82, v83
	v_add_f32_e32 v94, 0, v82
	ds_read_b128 v[82:85], v72 offset:26624
	ds_read_b128 v[90:93], v72 offset:26640
	v_pk_mul_f32 v[88:89], v[32:33], v[88:89]
	ds_bpermute_b32 v81, v165, v80
	v_pk_mov_b32 v[96:97], v[86:87], v[88:89] op_sel:[1,0]
	v_mov_b32_e32 v87, v89
	v_pk_add_f32 v[86:87], v[96:97], v[86:87]
	s_waitcnt lgkmcnt(1)
; #define LAS __attribute__((address_space(3)))
; template <int LO, int HI> __global__ void __launch_bounds__(NWAVES * 64, 2) fox_fwd(Args args) {
;     ...
;             for (int q = 0; q < 8; ++q) { float a = 0.f;
; #pragma unroll
;                 for (int j = 0; j < 4; ++j) { const f32x4 w = *(const LAS f32x4*)(wf + q * 1024 + P1COL(j)); a += (v[j][0] * w[0] + v[j][1] * w[1]) + (v[j][2] * w[2] + v[j][3] * w[3]); }
;                 fl[q] = wave_sum(a); }
;             float mine = fl[0];
; #pragma unroll
;             for (int q = 1; q < 8; ++q) mine = (lane == q) ? fl[q] : mine;
;             { const float z = mine + bfv; const float ls = fminf(z, 0.f) - log1pf(__expf(-fabsf(z)));
	v_mul_f32_e32 v88, v61, v91
	v_pk_add_f32 v[86:87], v[86:87], v[86:87] op_sel:[0,1] op_sel_hi:[1,0]
	v_mul_f32_e32 v95, v60, v90
	v_mov_b32_e32 v87, v88
	v_pk_add_f32 v[88:89], v[94:95], v[86:87]
	v_mul_f32_e32 v86, v31, v83
	v_pk_fma_f32 v[82:83], v[30:31], v[82:83], v[86:87] op_sel_hi:[1,1,0]
	v_mul_f32_e32 v86, v29, v85
	v_mul_f32_e32 v90, v58, v92
	v_mul_f32_e32 v91, v59, v93
	v_pk_fma_f32 v[84:85], v[28:29], v[84:85], v[86:87] op_sel_hi:[1,1,0]
	v_mov_b32_e32 v83, v90
	v_mov_b32_e32 v85, v91
	v_pk_add_f32 v[82:83], v[82:83], v[84:85]
	ds_read_b128 v[84:87], v72 offset:28672
	v_pk_add_f32 v[82:83], v[88:89], v[82:83]
	ds_read_b128 v[88:91], v72 offset:28688
	v_add_f32_e32 v82, v82, v83
	ds_bpermute_b32 v83, v165, v82
	s_waitcnt lgkmcnt(2)
	v_pk_mul_f32 v[64:65], v[64:65], v[84:85]
	v_pk_mul_f32 v[62:63], v[62:63], v[86:87]
	s_waitcnt lgkmcnt(1)
	v_pk_mul_f32 v[66:67], v[66:67], v[88:89]
	v_pk_mov_b32 v[84:85], v[64:65], v[62:63] op_sel:[1,0]
	v_mov_b32_e32 v65, v63
	v_pk_add_f32 v[62:63], v[84:85], v[64:65]
	v_pk_mul_f32 v[32:33], v[32:33], v[90:91]
	v_add_f32_e32 v62, v62, v63
	v_add_f32_e32 v92, 0, v62
	ds_read_b128 v[62:65], v72 offset:30720
	ds_read_b128 v[84:87], v72 offset:30736
	v_pk_mov_b32 v[88:89], v[66:67], v[32:33] op_sel:[1,0]
	v_mov_b32_e32 v67, v33
	v_pk_add_f32 v[32:33], v[88:89], v[66:67]
	ds_bpermute_b32 v77, v164, v76
	s_waitcnt lgkmcnt(1)
	v_mul_f32_e32 v93, v60, v84
	v_mul_f32_e32 v60, v61, v85
	v_mul_f32_e32 v61, v58, v86
	v_mul_f32_e32 v59, v59, v87
	v_mul_f32_e32 v58, v31, v63
	v_pk_fma_f32 v[30:31], v[30:31], v[62:63], v[58:59] op_sel_hi:[1,1,0]
	v_mul_f32_e32 v58, v29, v65
	v_pk_add_f32 v[32:33], v[32:33], v[32:33] op_sel:[0,1] op_sel_hi:[1,0]
	v_pk_fma_f32 v[28:29], v[28:29], v[64:65], v[58:59] op_sel_hi:[1,1,0]
	v_mov_b32_e32 v33, v60
	v_mov_b32_e32 v31, v61
	v_mov_b32_e32 v29, v59
	v_pk_add_f32 v[32:33], v[92:93], v[32:33]
	v_pk_add_f32 v[28:29], v[30:31], v[28:29]
	v_add_f32_e32 v30, v80, v81
	v_pk_add_f32 v[28:29], v[32:33], v[28:29]
	ds_bpermute_b32 v31, v169, v30
	v_add_f32_e32 v28, v28, v29
	ds_bpermute_b32 v29, v165, v28
	v_add_f32_e32 v32, v82, v83
	ds_bpermute_b32 v33, v169, v32
	s_waitcnt lgkmcnt(2)
	v_add_f32_e32 v30, v30, v31
	ds_bpermute_b32 v31, v168, v30
	s_waitcnt lgkmcnt(2)
	v_add_f32_e32 v28, v28, v29
	ds_bpermute_b32 v29, v169, v28
	s_waitcnt lgkmcnt(2)
	v_add_f32_e32 v32, v32, v33
	ds_bpermute_b32 v33, v168, v32
	s_waitcnt lgkmcnt(2)
	v_add_f32_e32 v30, v30, v31
	ds_bpermute_b32 v31, v167, v30
	s_waitcnt lgkmcnt(2)
	v_add_f32_e32 v28, v28, v29
	ds_bpermute_b32 v29, v168, v28
	s_waitcnt lgkmcnt(2)
	v_add_f32_e32 v32, v32, v33
	ds_bpermute_b32 v33, v167, v32
	s_waitcnt lgkmcnt(2)
	v_add_f32_e32 v30, v30, v31
	ds_bpermute_b32 v31, v166, v30
	s_waitcnt lgkmcnt(2)
	v_add_f32_e32 v28, v28, v29
	ds_bpermute_b32 v29, v167, v28
	s_waitcnt lgkmcnt(2)
	v_add_f32_e32 v32, v32, v33
	ds_bpermute_b32 v33, v166, v32
	ds_bpermute_b32 v79, v164, v78
	s_waitcnt lgkmcnt(3)
	v_add_f32_e32 v30, v30, v31
	s_waitcnt lgkmcnt(2)
	v_add_f32_e32 v28, v28, v29
	ds_bpermute_b32 v29, v166, v28
	ds_bpermute_b32 v31, v164, v30
	s_waitcnt lgkmcnt(3)
	v_add_f32_e32 v32, v32, v33
	ds_bpermute_b32 v33, v164, v32
	v_add_f32_e32 v58, v76, v77
	s_waitcnt lgkmcnt(2)
	v_add_f32_e32 v28, v28, v29
	ds_bpermute_b32 v29, v164, v28
	v_add_f32_e32 v59, v78, v79
	s_waitcnt lgkmcnt(2)
	v_add_f32_e32 v30, v30, v31
	s_waitcnt lgkmcnt(1)
	v_add_f32_e32 v31, v32, v33
	global_store_dwordx4 v[24:25], v[18:21], off offset:1024
	s_waitcnt lgkmcnt(0)
	v_add_f32_e32 v28, v28, v29
	v_cndmask_b32_e64 v29, v57, v74, s[4:5]
	v_cndmask_b32_e64 v29, v29, v75, s[6:7]
	v_cndmask_b32_e64 v29, v29, v58, s[8:9]
	v_cndmask_b32_e64 v29, v29, v59, s[10:11]
	v_cndmask_b32_e64 v29, v29, v30, s[12:13]
	v_cndmask_b32_e64 v29, v29, v31, s[14:15]
	v_cndmask_b32_e64 v28, v29, v28, s[16:17]
	v_add_f32_e32 v29, v71, v28
	v_mul_f32_e64 v28, |v29|, s29
	v_exp_f32_e32 v78, v28
	v_ldexp_f32 v28, v23, v27
	v_min_f32_e32 v23, 0, v29
	v_add_f32_e32 v20, 1.0, v78
	v_add_f32_e32 v18, -1.0, v20
	v_sub_f32_e32 v19, v18, v20
	v_add_f32_e32 v19, 1.0, v19
	v_sub_f32_e32 v18, v78, v18
	v_add_f32_e32 v21, v18, v19
	v_frexp_mant_f32_e32 v24, v20
	v_cvt_f64_f32_e32 v[18:19], v20
	v_frexp_exp_i32_f64_e32 v18, v[18:19]
	v_cmp_gt_f32_e32 vcc, s37, v24
	s_nop 1
	v_subbrev_co_u32_e32 v57, vcc, 0, v18, vcc
	v_sub_u32_e32 v18, 0, v57
	v_ldexp_f32 v27, v20, v18
	v_ldexp_f32 v29, v21, v18
	v_pk_add_f32 v[18:19], v[26:27], 1.0 op_sel_hi:[1,0]
	v_pk_add_f32 v[32:33], v[26:27], -1.0 op_sel_hi:[1,0]
	v_pk_add_f32 v[20:21], v[18:19], -1.0 op_sel_hi:[1,0]
	v_pk_add_f32 v[58:59], v[32:33], 1.0 op_sel_hi:[1,0]
	v_pk_add_f32 v[20:21], v[26:27], v[20:21] neg_lo:[0,1] neg_hi:[0,1]
	v_pk_add_f32 v[26:27], v[26:27], v[58:59] neg_lo:[0,1] neg_hi:[0,1]
	v_pk_add_f32 v[20:21], v[28:29], v[20:21]
	v_pk_add_f32 v[26:27], v[28:29], v[26:27]
	v_pk_add_f32 v[24:25], v[18:19], v[20:21]
	v_pk_add_f32 v[28:29], v[32:33], v[26:27]
	v_rcp_f32_e32 v30, v24
	v_rcp_f32_e32 v31, v25
	v_pk_add_f32 v[18:19], v[24:25], v[18:19] neg_lo:[0,1] neg_hi:[0,1]
	v_pk_add_f32 v[32:33], v[28:29], v[32:33] neg_lo:[0,1] neg_hi:[0,1]
	v_pk_add_f32 v[18:19], v[20:21], v[18:19] neg_lo:[0,1] neg_hi:[0,1]
	v_pk_mul_f32 v[20:21], v[28:29], v[30:31]
	v_pk_add_f32 v[26:27], v[26:27], v[32:33] neg_lo:[0,1] neg_hi:[0,1]
	v_pk_mul_f32 v[32:33], v[24:25], v[20:21]
	v_cmp_neq_f32_e32 vcc, s46, v55
	v_pk_fma_f32 v[58:59], v[20:21], v[24:25], v[32:33] neg_lo:[0,0,1] neg_hi:[0,0,1]
	s_nop 0
	v_pk_fma_f32 v[58:59], v[20:21], v[18:19], v[58:59]
	s_nop 0
	v_pk_add_f32 v[60:61], v[32:33], v[58:59]
	s_nop 0
	v_pk_add_f32 v[62:63], v[28:29], v[60:61] neg_lo:[0,1] neg_hi:[0,1]
; template <int LO, int HI> __global__ void __launch_bounds__(NWAVES * 64, 2) fox_fwd(Args args) {
;     ...
;             { const float z = mine + bfv; const float ls = fminf(z, 0.f) - log1pf(__expf(-fabsf(z)));
; #pragma unroll
;               for (int k = 0; k < 4; ++k)
; #pragma unroll
;                   for (int e = 0; e < 4; ++e) lsq[k][e] = (r == 4 * k + e) ? ls : lsq[k][e]; }
	v_pk_add_f32 v[32:33], v[60:61], v[32:33] neg_lo:[0,1] neg_hi:[0,1]
	v_pk_add_f32 v[28:29], v[28:29], v[62:63] neg_lo:[0,1] neg_hi:[0,1]
	s_nop 0
	v_pk_add_f32 v[28:29], v[28:29], v[60:61] neg_lo:[0,1] neg_hi:[0,1]
	s_nop 0
	v_pk_add_f32 v[26:27], v[26:27], v[28:29]
	v_pk_add_f32 v[28:29], v[32:33], v[58:59] neg_lo:[0,1] neg_hi:[0,1]
	s_nop 0
	v_pk_add_f32 v[26:27], v[28:29], v[26:27]
	s_nop 0
	v_pk_add_f32 v[28:29], v[62:63], v[26:27]
	s_nop 0
	v_pk_mul_f32 v[32:33], v[30:31], v[28:29]
	s_nop 0
	v_pk_mul_f32 v[58:59], v[24:25], v[32:33]
	s_nop 0
	v_pk_fma_f32 v[24:25], v[32:33], v[24:25], v[58:59] neg_lo:[0,0,1] neg_hi:[0,0,1]
	s_nop 0
	v_pk_fma_f32 v[18:19], v[32:33], v[18:19], v[24:25]
	v_pk_add_f32 v[24:25], v[62:63], v[28:29] neg_lo:[0,1] neg_hi:[0,1]
	s_nop 0
	v_pk_add_f32 v[24:25], v[26:27], v[24:25]
	v_pk_add_f32 v[26:27], v[58:59], v[18:19]
	s_nop 0
	v_pk_add_f32 v[60:61], v[28:29], v[26:27] neg_lo:[0,1] neg_hi:[0,1]
	v_pk_add_f32 v[58:59], v[26:27], v[58:59] neg_lo:[0,1] neg_hi:[0,1]
	v_pk_add_f32 v[28:29], v[28:29], v[60:61] neg_lo:[0,1] neg_hi:[0,1]
	v_pk_add_f32 v[18:19], v[58:59], v[18:19] neg_lo:[0,1] neg_hi:[0,1]
	v_pk_add_f32 v[26:27], v[28:29], v[26:27] neg_lo:[0,1] neg_hi:[0,1]
	s_nop 0
	v_pk_add_f32 v[24:25], v[24:25], v[26:27]
	s_nop 0
	v_pk_add_f32 v[18:19], v[18:19], v[24:25]
	v_pk_add_f32 v[24:25], v[20:21], v[32:33]
	v_pk_add_f32 v[18:19], v[60:61], v[18:19]
	v_pk_add_f32 v[20:21], v[24:25], v[20:21] neg_lo:[0,1] neg_hi:[0,1]
	v_pk_mul_f32 v[18:19], v[30:31], v[18:19]
	v_pk_add_f32 v[20:21], v[32:33], v[20:21] neg_lo:[0,1] neg_hi:[0,1]
	v_cvt_f32_i32_e32 v32, v56
	v_pk_add_f32 v[18:19], v[20:21], v[18:19]
	v_cvt_f32_i32_e32 v33, v57
	v_pk_add_f32 v[26:27], v[24:25], v[18:19]
	s_nop 0
	v_pk_add_f32 v[20:21], v[26:27], v[24:25] neg_lo:[0,1] neg_hi:[0,1]
	v_pk_mul_f32 v[28:29], v[26:27], v[26:27]
	v_pk_add_f32 v[18:19], v[18:19], v[20:21] neg_lo:[0,1] neg_hi:[0,1]
	v_mov_b32_e32 v20, 0x3ecc95a3
	v_pk_fma_f32 v[30:31], v[28:29], s[20:21], v[20:21] op_sel_hi:[1,0,0]
	s_mov_b32 s20, 0x3f2aaada
	v_ldexp_f32 v24, v26, 1
	v_pk_fma_f32 v[30:31], v[28:29], v[30:31], s[20:21] op_sel_hi:[1,1,0]
	v_ldexp_f32 v25, v27, 1
	v_pk_mul_f32 v[26:27], v[26:27], v[28:29]
	v_pk_mul_f32 v[28:29], v[32:33], s[36:37] op_sel_hi:[1,0]
	v_pk_mul_f32 v[26:27], v[26:27], v[30:31]
	v_pk_fma_f32 v[58:59], v[32:33], s[36:37], v[28:29] op_sel_hi:[1,0,1] neg_lo:[0,0,1] neg_hi:[0,0,1]
	v_pk_add_f32 v[30:31], v[24:25], v[26:27]
	s_mov_b32 s20, 0xb102e308
	v_pk_add_f32 v[24:25], v[30:31], v[24:25] neg_lo:[0,1] neg_hi:[0,1]
	v_ldexp_f32 v57, v19, 1
	v_pk_fma_f32 v[32:33], v[32:33], s[20:21], v[58:59] op_sel_hi:[1,0,1]
	v_pk_add_f32 v[24:25], v[26:27], v[24:25] neg_lo:[0,1] neg_hi:[0,1]
	v_ldexp_f32 v18, v18, 1
	v_mov_b32_e32 v26, v28
	v_mov_b32_e32 v27, v25
	v_mov_b32_e32 v56, v32
	v_mov_b32_e32 v19, v57
	v_pk_add_f32 v[26:27], v[26:27], v[56:57]
	v_pk_add_f32 v[56:57], v[18:19], v[24:25]
	v_mov_b32_e32 v25, v31
	v_mov_b32_e32 v19, v57
	v_pk_add_f32 v[58:59], v[28:29], v[32:33]
	v_pk_add_f32 v[18:19], v[18:19], v[24:25]
	v_pk_add_f32 v[24:25], v[30:31], v[56:57]
	v_mov_b32_e32 v74, v30
	v_pk_add_f32 v[60:61], v[58:59], v[24:25]
	v_mov_b32_e32 v66, v24
	v_mov_b32_e32 v67, v61
	v_mov_b32_e32 v75, v59
	v_pk_add_f32 v[66:67], v[66:67], v[74:75] neg_lo:[0,1] neg_hi:[0,1]
	v_mov_b32_e32 v62, v60
	v_mov_b32_e32 v63, v59
	v_mov_b32_e32 v64, v58
	v_mov_b32_e32 v65, v29
	v_mov_b32_e32 v74, v58
	v_mov_b32_e32 v75, v61
	v_mov_b32_e32 v29, v67
	v_pk_add_f32 v[62:63], v[62:63], v[64:65] neg_lo:[0,1] neg_hi:[0,1]
	v_mov_b32_e32 v64, v24
	v_mov_b32_e32 v65, v33
	v_pk_add_f32 v[28:29], v[74:75], v[28:29] neg_lo:[0,1] neg_hi:[0,1]
	v_pk_add_f32 v[64:65], v[64:65], v[62:63] neg_lo:[0,1] neg_hi:[0,1]
	v_mov_b32_e32 v74, v28
	v_mov_b32_e32 v75, v63
	v_mov_b32_e32 v76, v60
	v_mov_b32_e32 v77, v25
	v_mov_b32_e32 v63, v31
	v_pk_add_f32 v[74:75], v[32:33], v[74:75] neg_lo:[0,1] neg_hi:[0,1]
	v_pk_add_f32 v[62:63], v[76:77], v[62:63] neg_lo:[0,1] neg_hi:[0,1]
	v_mov_b32_e32 v33, v59
	v_pk_add_f32 v[26:27], v[26:27], v[62:63] neg_lo:[0,1] neg_hi:[0,1]
	v_pk_add_f32 v[28:29], v[32:33], v[28:29] neg_lo:[0,1] neg_hi:[0,1]
	v_pk_add_f32 v[18:19], v[18:19], v[66:67] neg_lo:[0,1] neg_hi:[0,1]
	v_pk_add_f32 v[24:25], v[24:25], v[30:31] neg_lo:[0,1] neg_hi:[0,1]
	v_pk_add_f32 v[30:31], v[18:19], v[28:29]
	v_mov_b32_e32 v29, v65
	v_mov_b32_e32 v19, v27
	v_pk_add_f32 v[32:33], v[64:65], v[26:27]
	v_pk_add_f32 v[18:19], v[28:29], v[18:19]
	v_mov_b32_e32 v26, v30
	v_pk_add_f32 v[18:19], v[18:19], v[74:75] neg_lo:[0,1] neg_hi:[0,1]
	v_mov_b32_e32 v27, v33
	v_pk_add_f32 v[24:25], v[56:57], v[24:25] neg_lo:[0,1] neg_hi:[0,1]
	v_pk_add_f32 v[26:27], v[26:27], v[18:19] neg_lo:[0,1] neg_hi:[0,1]
	v_pk_add_f32 v[18:19], v[24:25], v[18:19] neg_lo:[0,1] neg_hi:[0,1]
	v_pk_add_f32 v[26:27], v[28:29], v[26:27] neg_lo:[0,1] neg_hi:[0,1]
	v_pk_add_f32 v[24:25], v[32:33], v[30:31]
	v_pk_add_f32 v[18:19], v[18:19], v[26:27]
	v_pk_add_f32 v[26:27], v[60:61], v[24:25]
	v_mov_b32_e32 v64, 0x7f800000
	v_pk_add_f32 v[28:29], v[26:27], v[60:61] neg_lo:[0,1] neg_hi:[0,1]
	v_mov_b32_e32 v65, 0x7fc00000
	v_pk_add_f32 v[24:25], v[24:25], v[28:29] neg_lo:[0,1] neg_hi:[0,1]
	v_mov_b32_e32 v66, 0xff800000
	v_pk_add_f32 v[18:19], v[18:19], v[24:25]
	s_add_u32 s20, s26, s34
	v_pk_add_f32 v[18:19], v[26:27], v[18:19]
	s_addc_u32 s21, s27, s35
	v_cndmask_b32_e32 v18, v64, v18, vcc
	v_cmp_neq_f32_e32 vcc, s46, v78
	s_mov_b64 s[34:35], 0x2000
	v_mov_b32_e32 v58, 0x3f317218
	v_cndmask_b32_e32 v19, v64, v19, vcc
	v_cmp_ngt_f32_e32 vcc, -1.0, v78
	v_mov_b32_e32 v21, v37
	v_mov_b32_e32 v30, v37
	v_cndmask_b32_e32 v19, v65, v19, vcc
; #define GAS __attribute__((address_space(1)))
; template <int LO, int HI> __global__ void __launch_bounds__(NWAVES * 64, 2) fox_fwd(Args args) {
;     ...
;         for (int r = 0; r < 16; ++r) { const int m = m0 + r;
;             const GAS float* xr = (const GAS float*)(x + (size_t)m * D);
;             f32x4 v[4]; float s2 = 0.f;
; #pragma unroll
;             for (int j = 0; j < 4; ++j) { v[j] = *(const GAS f32x4*)(xr + P1COL(j)); s2 += (v[j][0] * v[j][0] + v[j][1] * v[j][1]) + (v[j][2] * v[j][2] + v[j][3] * v[j][3]); }
;     ...
;             { const float z = mine + bfv; const float ls = fminf(z, 0.f) - log1pf(__expf(-fabsf(z)));
; #pragma unroll
;               for (int k = 0; k < 4; ++k)
; #pragma unroll
;                   for (int e = 0; e < 4; ++e) lsq[k][e] = (r == 4 * k + e) ? ls : lsq[k][e]; }
	v_cmp_ngt_f32_e32 vcc, -1.0, v55
	v_mov_b32_e32 v31, v37
	v_mov_b32_e32 v32, v37
	v_cndmask_b32_e32 v18, v65, v18, vcc
	v_cmp_neq_f32_e32 vcc, -1.0, v55
	v_mov_b32_e32 v33, v37
	v_mov_b32_e32 v26, v37
	v_cndmask_b32_e32 v18, v66, v18, vcc
	v_cmp_neq_f32_e32 vcc, -1.0, v78
	v_mov_b32_e32 v27, v37
	v_mov_b32_e32 v28, v37
	v_cndmask_b32_e32 v19, v66, v19, vcc
	v_cmp_lt_f32_e64 vcc, |v78|, s47
	v_mov_b32_e32 v29, v37
	v_mov_b32_e32 v24, v37
	v_cndmask_b32_e32 v19, v19, v78, vcc
	v_cmp_lt_f32_e64 vcc, |v55|, s47
	v_mov_b32_e32 v25, v37
	s_nop 0
	v_cndmask_b32_e32 v18, v18, v55, vcc
	v_pk_add_f32 v[18:19], v[22:23], v[18:19] neg_lo:[0,1] neg_hi:[0,1]
	v_mov_b32_e32 v55, v37
	v_lshl_add_u64 v[22:23], s[20:21], 0, v[36:37]
	s_mov_b64 s[20:21], 0x2001400
	v_lshl_add_u64 v[54:55], s[30:31], 0, v[54:55]
	v_lshl_add_u64 v[56:57], v[22:23], 0, s[20:21]
	s_mov_b64 s[30:31], 0
	v_mov_b32_e32 v22, v37
	v_mov_b32_e32 v23, v37
	ds_read_b128 v[100:103], v72
	ds_read_b128 v[104:107], v72 offset:16
	ds_read_b128 v[108:111], v72 offset:2048
	ds_read_b128 v[112:115], v72 offset:2064
	ds_read_b128 v[116:119], v72 offset:4096
	ds_read_b128 v[120:123], v72 offset:4112
	ds_read_b128 v[124:127], v72 offset:6144
	ds_read_b128 v[128:131], v72 offset:6160
	ds_read_b128 v[132:135], v72 offset:8192
	ds_read_b128 v[136:139], v72 offset:8208
	ds_read_b128 v[140:143], v72 offset:10240
	ds_read_b128 v[144:147], v72 offset:10256
	s_waitcnt lgkmcnt(0)
	ds_read_b128 v[148:151], v72 offset:12288
	ds_read_b128 v[152:155], v72 offset:12304
	ds_read_b128 v[156:159], v72 offset:14336
	ds_read_b128 v[170:173], v72 offset:14352
	ds_read_b128 v[174:177], v72 offset:16384
	ds_read_b128 v[178:181], v72 offset:16400
	ds_read_b128 v[182:185], v72 offset:18432
	ds_read_b128 v[186:189], v72 offset:18448
	ds_read_b128 v[190:193], v72 offset:20480
	ds_read_b128 v[194:197], v72 offset:20496
	ds_read_b128 v[198:201], v72 offset:22528
	ds_read_b128 v[202:205], v72 offset:22544
	s_waitcnt lgkmcnt(0)
	ds_read_b128 v[206:209], v72 offset:24576
	ds_read_b128 v[210:213], v72 offset:24592
	ds_read_b128 v[226:229], v72 offset:26624
	ds_read_b128 v[230:233], v72 offset:26640
	ds_read_b128 v[234:237], v72 offset:28672
	ds_read_b128 v[238:241], v72 offset:28688
	ds_read_b128 v[242:245], v72 offset:30720
	ds_read_b128 v[246:249], v72 offset:30736
	s_waitcnt lgkmcnt(0)
	s_mov_b32 s52, m0
	s_mov_b64 s[56:57], 0x2000
	s_mov_b64 s[58:59], 16
	s_mov_b64 s[60:61], 0x800
	v_lshrrev_b32_e32 v224, 6, v0
	v_mbcnt_lo_u32_b32 v225, -1, 0
	v_mbcnt_hi_u32_b32 v225, -1, v225
	v_readfirstlane_b32 s50, v224
	v_lshlrev_b32_e32 v224, 4, v225
	s_lshl_b32 s50, s50, 12
	s_add_i32 s50, s50, 0x11000
	s_mov_b32 s53, 0
	v_mov_b32_e32 v160, s53
	v_mov_b32_e32 v161, 0
	v_lshl_add_u64 v[160:161], v[54:55], 0, v[160:161]
	v_lshl_add_u64 v[250:251], v[160:161], 0, s[56:57]
	v_lshl_add_u64 v[252:253], v[160:161], 0, s[34:35]
	v_lshl_add_u64 v[254:255], v[160:161], 0, s[38:39]
	v_lshl_add_u64 v[252:253], v[252:253], 0, s[58:59]
	v_lshl_add_u64 v[254:255], v[254:255], 0, s[58:59]
	v_lshl_add_u64 v[160:161], v[250:251], 0, s[60:61]
	s_mov_b32 m0, s50
	s_nop 0
	global_load_lds_dwordx4 v[250:251], off
	s_add_i32 m0, s50, 0x400
	s_nop 0
	global_load_lds_dwordx4 v[252:253], off
	s_add_i32 m0, s50, 0x800
	s_nop 0
	global_load_lds_dwordx4 v[254:255], off
	s_add_i32 m0, s50, 0xc00
	s_nop 0
	global_load_lds_dwordx4 v[160:161], off
.LBB0_131:
	s_waitcnt vmcnt(0)
	s_barrier
	v_add_u32_e32 v225, s50, v224
	ds_read_b128 v[60:63], v225
	ds_read_b128 v[74:77], v225 offset:1024
	ds_read_b128 v[78:81], v225 offset:2048
	ds_read_b128 v[82:85], v225 offset:3072
	s_waitcnt lgkmcnt(0)
	s_cmp_eq_u32 s30, 0xd000
	s_cbranch_scc1 .Lp1dma_skip
	s_add_i32 s53, s30, 0x1000
	v_mov_b32_e32 v160, s53
	v_mov_b32_e32 v161, 0
	v_lshl_add_u64 v[160:161], v[54:55], 0, v[160:161]
	v_lshl_add_u64 v[250:251], v[160:161], 0, s[56:57]
	v_lshl_add_u64 v[252:253], v[160:161], 0, s[34:35]
	v_lshl_add_u64 v[254:255], v[160:161], 0, s[38:39]
	v_lshl_add_u64 v[252:253], v[252:253], 0, s[58:59]
	v_lshl_add_u64 v[254:255], v[254:255], 0, s[58:59]
	v_lshl_add_u64 v[160:161], v[250:251], 0, s[60:61]
	s_mov_b32 m0, s50
	s_nop 0
	global_load_lds_dwordx4 v[250:251], off
	s_add_i32 m0, s50, 0x400
	s_nop 0
	global_load_lds_dwordx4 v[252:253], off
	s_add_i32 m0, s50, 0x800
	s_nop 0
	global_load_lds_dwordx4 v[254:255], off
	s_add_i32 m0, s50, 0xc00
	s_nop 0
	global_load_lds_dwordx4 v[160:161], off
; #define GAS __attribute__((address_space(1)))
; #define LAS __attribute__((address_space(3)))
; __device__ __forceinline__ unsigned pk2(float lo, float hi) { return pg8::cvt_pk_bf16(lo, hi); }
; template <int LO, int HI> __global__ void __launch_bounds__(NWAVES * 64, 2) fox_fwd(Args args) {
;     ...
;         for (int r = 0; r < 16; ++r) { const int m = m0 + r;
;             const GAS float* xr = (const GAS float*)(x + (size_t)m * D);
;             f32x4 v[4]; float s2 = 0.f;
; #pragma unroll
;             for (int j = 0; j < 4; ++j) { v[j] = *(const GAS f32x4*)(xr + P1COL(j)); s2 += (v[j][0] * v[j][0] + v[j][1] * v[j][1]) + (v[j][2] * v[j][2] + v[j][3] * v[j][3]); }
;             const float rstd = 1.0f / sqrtf(wave_sum(s2) * (1.0f / D) + EPS);
; #pragma unroll
;             for (int j = 0; j < 4; ++j) v[j] = v[j] * rstd * gm[j] + sh[j];
; #pragma unroll
;             for (int j = 0; j < 2; ++j) { v4u o; o.x = pk2(v[2 * j][0], v[2 * j][1]); o.y = pk2(v[2 * j][2], v[2 * j][3]); o.z = pk2(v[2 * j + 1][0], v[2 * j + 1][1]); o.w = pk2(v[2 * j + 1][2], v[2 * j + 1][3]);
;                 *(GAS v4u*)(HB + (size_t)m * D + 8 * lane + 512 * j) = o; }
;             float fl[8];
; #pragma unroll
;             for (int q = 0; q < 8; ++q) { float a = 0.f;
; #pragma unroll
;                 for (int j = 0; j < 4; ++j) { const f32x4 w = *(const LAS f32x4*)(wf + q * 1024 + P1COL(j)); a += (v[j][0] * w[0] + v[j][1] * w[1]) + (v[j][2] * w[2] + v[j][3] * w[3]); }
;                 fl[q] = wave_sum(a); }
.Lp1dma_skip:
	s_cmp_eq_u32 s30, 0
	v_pk_mul_f32 v[86:87], v[62:63], v[62:63]
	v_pk_mul_f32 v[88:89], v[60:61], v[60:61]
	v_pk_mul_f32 v[90:91], v[76:77], v[76:77]
	v_pk_mul_f32 v[92:93], v[74:75], v[74:75]
	v_pk_mov_b32 v[96:97], v[88:89], v[86:87] op_sel:[1,0]
	v_mov_b32_e32 v89, v87
	v_pk_mov_b32 v[86:87], v[92:93], v[90:91] op_sel:[1,0]
	v_mov_b32_e32 v93, v91
	v_mul_f32_e32 v36, v83, v83
	v_mul_f32_e32 v94, v85, v85
	v_pk_add_f32 v[88:89], v[96:97], v[88:89]
	v_pk_add_f32 v[86:87], v[86:87], v[92:93]
	v_mul_f32_e32 v59, v78, v78
	v_mul_f32_e32 v67, v79, v79
	v_mul_f32_e32 v98, v80, v80
	v_mul_f32_e32 v99, v81, v81
	v_pk_fma_f32 v[90:91], v[82:83], v[82:83], v[36:37] op_sel_hi:[1,1,0]
	v_pk_fma_f32 v[94:95], v[84:85], v[84:85], v[94:95] op_sel_hi:[1,1,0]
	v_pk_add_f32 v[88:89], v[88:89], v[88:89] op_sel:[0,1] op_sel_hi:[1,0]
	v_pk_add_f32 v[86:87], v[86:87], v[86:87] op_sel:[0,1] op_sel_hi:[1,0]
	v_mov_b32_e32 v91, v98
	v_mov_b32_e32 v95, v99
	v_mov_b32_e32 v89, v59
	v_mov_b32_e32 v87, v67
	v_pk_add_f32 v[90:91], v[90:91], v[94:95]
	v_pk_add_f32 v[86:87], v[88:89], v[86:87]
	s_nop 0
	v_pk_add_f32 v[86:87], v[86:87], v[90:91]
	s_nop 0
	v_add_f32_e32 v36, v86, v87
	s_waitcnt lgkmcnt(0)
	s_nop 1
	v_add_f32_dpp v59, v36, v36 quad_perm:[1,0,3,2] row_mask:0xf bank_mask:0xf
	s_nop 1
	v_add_f32_dpp v36, v59, v59 quad_perm:[2,3,0,1] row_mask:0xf bank_mask:0xf
	s_nop 1
	v_add_f32_dpp v59, v36, v36 row_half_mirror row_mask:0xf bank_mask:0xf
	s_nop 1
	v_add_f32_dpp v36, v59, v59 row_mirror row_mask:0xf bank_mask:0xf
	v_mov_b32_e32 v59, v36
	s_nop 1
	v_permlane16_swap_b32_e32 v59, v36
	v_add_f32_e32 v59, v59, v36
	v_mov_b32_e32 v36, v59
	s_nop 1
	v_permlane32_swap_b32_e32 v36, v59
	v_add_f32_e32 v36, v36, v59
	v_fmamk_f32 v36, v36, 0x3a800000, v69
	v_mul_f32_e32 v59, 0x4f800000, v36
	v_cmp_gt_f32_e32 vcc, s45, v36
	s_nop 1
	v_cndmask_b32_e32 v36, v36, v59, vcc
	v_sqrt_f32_e32 v59, v36
	s_nop 0
	v_add_u32_e32 v67, -1, v59
	v_add_u32_e32 v86, 1, v59
	v_fma_f32 v87, -v67, v59, v36
	v_fma_f32 v88, -v86, v59, v36
	v_cmp_ge_f32_e64 s[20:21], 0, v87
	s_nop 1
	v_cndmask_b32_e64 v59, v59, v67, s[20:21]
	v_cmp_lt_f32_e64 s[20:21], 0, v88
	s_nop 1
	v_cndmask_b32_e64 v59, v59, v86, s[20:21]
	v_mul_f32_e32 v67, 0x37800000, v59
	v_cndmask_b32_e32 v59, v59, v67, vcc
	v_cmp_class_f32_e32 vcc, v36, v70
	s_nop 1
	v_cndmask_b32_e32 v36, v59, v36, vcc
	v_div_scale_f32 v59, s[20:21], v36, v36, 1.0
	v_rcp_f32_e32 v86, v59
	v_div_scale_f32 v67, vcc, 1.0, v36, 1.0
	v_fma_f32 v87, -v59, v86, 1.0
	v_fmac_f32_e32 v86, v87, v86
	v_mul_f32_e32 v87, v67, v86
	v_fma_f32 v88, -v59, v87, v67
	v_fmac_f32_e32 v87, v88, v86
	v_fma_f32 v59, -v59, v87, v67
	v_div_fmas_f32 v59, v59, v86, v87
	v_div_fixup_f32 v36, v59, v36, 1.0
	v_pk_mul_f32 v[60:61], v[36:37], v[60:61] op_sel_hi:[0,1]
	v_pk_mul_f32 v[62:63], v[36:37], v[62:63] op_sel_hi:[0,1]
	v_pk_mul_f32 v[74:75], v[36:37], v[74:75] op_sel_hi:[0,1]
	v_pk_mul_f32 v[76:77], v[36:37], v[76:77] op_sel_hi:[0,1]
	v_pk_mul_f32 v[82:83], v[36:37], v[82:83] op_sel_hi:[0,1]
	v_pk_mul_f32 v[84:85], v[36:37], v[84:85] op_sel_hi:[0,1]
	v_pk_mul_f32 v[78:79], v[36:37], v[78:79] op_sel_hi:[0,1]
	v_pk_mul_f32 v[80:81], v[36:37], v[80:81] op_sel_hi:[0,1]
	v_pk_fma_f32 v[162:163], v[38:39], v[62:63], v[8:9]
	v_pk_fma_f32 v[214:215], v[40:41], v[60:61], v[6:7]
	v_pk_fma_f32 v[216:217], v[42:43], v[76:77], v[4:5]
	v_pk_fma_f32 v[218:219], v[44:45], v[74:75], v[2:3]
	v_cvt_pk_bf16_f32 v74, v214, v215
	v_cvt_pk_bf16_f32 v75, v162, v163
	v_pk_fma_f32 v[60:61], v[46:47], v[84:85], v[16:17]
	v_cvt_pk_bf16_f32 v76, v218, v219
	v_cvt_pk_bf16_f32 v77, v216, v217
	v_pk_fma_f32 v[62:63], v[48:49], v[82:83], v[14:15]
	v_pk_fma_f32 v[220:221], v[50:51], v[80:81], v[12:13]
	v_pk_fma_f32 v[222:223], v[52:53], v[78:79], v[10:11]
	global_store_dwordx4 v[56:57], v[74:77], off offset:-1024
	s_nop 1
	v_cvt_pk_bf16_f32 v74, v62, v63
	v_cvt_pk_bf16_f32 v75, v60, v61
	v_cvt_pk_bf16_f32 v76, v222, v223
	v_cvt_pk_bf16_f32 v77, v220, v221
	s_nop 0
	global_store_dwordx4 v[56:57], v[74:77], off
	v_mul_f32_e32 v36, v214, v100
	v_mul_f32_e32 v59, v214, v116
	v_mul_f32_e32 v67, v214, v132
	v_mul_f32_e32 v74, v214, v148
	v_mul_f32_e32 v75, v214, v174
	v_mul_f32_e32 v76, v214, v190
	v_mul_f32_e32 v77, v214, v206
	v_mul_f32_e32 v250, v214, v234
	v_fmac_f32_e32 v36, v215, v101
	v_fmac_f32_e32 v59, v215, v117
	v_fmac_f32_e32 v67, v215, v133
	v_fmac_f32_e32 v74, v215, v149
	v_fmac_f32_e32 v75, v215, v175
	v_fmac_f32_e32 v76, v215, v191
	v_fmac_f32_e32 v77, v215, v207
	v_fmac_f32_e32 v250, v215, v235
	v_fmac_f32_e32 v36, v162, v102
	v_fmac_f32_e32 v59, v162, v118
	v_fmac_f32_e32 v67, v162, v134
	v_fmac_f32_e32 v74, v162, v150
	v_fmac_f32_e32 v75, v162, v176
	v_fmac_f32_e32 v76, v162, v192
	v_fmac_f32_e32 v77, v162, v208
	v_fmac_f32_e32 v250, v162, v236
	v_fmac_f32_e32 v36, v163, v103
	v_fmac_f32_e32 v59, v163, v119
	v_fmac_f32_e32 v67, v163, v135
	v_fmac_f32_e32 v74, v163, v151
	v_fmac_f32_e32 v75, v163, v177
	v_fmac_f32_e32 v76, v163, v193
	v_fmac_f32_e32 v77, v163, v209
	v_fmac_f32_e32 v250, v163, v237
	v_fmac_f32_e32 v36, v218, v104
	v_fmac_f32_e32 v59, v218, v120
	v_fmac_f32_e32 v67, v218, v136
	v_fmac_f32_e32 v74, v218, v152
	v_fmac_f32_e32 v75, v218, v178
	v_fmac_f32_e32 v76, v218, v194
	v_fmac_f32_e32 v77, v218, v210
	v_fmac_f32_e32 v250, v218, v238
	v_fmac_f32_e32 v36, v219, v105
	v_fmac_f32_e32 v59, v219, v121
	v_fmac_f32_e32 v67, v219, v137
	v_fmac_f32_e32 v74, v219, v153
	v_fmac_f32_e32 v75, v219, v179
	v_fmac_f32_e32 v76, v219, v195
	v_fmac_f32_e32 v77, v219, v211
	v_fmac_f32_e32 v250, v219, v239
	v_fmac_f32_e32 v36, v216, v106
	v_fmac_f32_e32 v59, v216, v122
; #define LAS __attribute__((address_space(3)))
; template <int LO, int HI> __global__ void __launch_bounds__(NWAVES * 64, 2) fox_fwd(Args args) {
;     ...
;             for (int q = 0; q < 8; ++q) { float a = 0.f;
; #pragma unroll
;                 for (int j = 0; j < 4; ++j) { const f32x4 w = *(const LAS f32x4*)(wf + q * 1024 + P1COL(j)); a += (v[j][0] * w[0] + v[j][1] * w[1]) + (v[j][2] * w[2] + v[j][3] * w[3]); }
;                 fl[q] = wave_sum(a); }
	v_fmac_f32_e32 v67, v216, v138
	v_fmac_f32_e32 v74, v216, v154
	v_fmac_f32_e32 v75, v216, v180
	v_fmac_f32_e32 v76, v216, v196
	v_fmac_f32_e32 v77, v216, v212
	v_fmac_f32_e32 v250, v216, v240
	v_fmac_f32_e32 v36, v217, v107
	v_fmac_f32_e32 v59, v217, v123
	v_fmac_f32_e32 v67, v217, v139
	v_fmac_f32_e32 v74, v217, v155
	v_fmac_f32_e32 v75, v217, v181
	v_fmac_f32_e32 v76, v217, v197
	v_fmac_f32_e32 v77, v217, v213
	v_fmac_f32_e32 v250, v217, v241
	v_fmac_f32_e32 v36, v62, v108
	v_fmac_f32_e32 v59, v62, v124
	v_fmac_f32_e32 v67, v62, v140
	v_fmac_f32_e32 v74, v62, v156
	v_fmac_f32_e32 v75, v62, v182
	v_fmac_f32_e32 v76, v62, v198
	v_fmac_f32_e32 v77, v62, v226
	v_fmac_f32_e32 v250, v62, v242
	v_fmac_f32_e32 v36, v63, v109
	v_fmac_f32_e32 v59, v63, v125
	v_fmac_f32_e32 v67, v63, v141
	v_fmac_f32_e32 v74, v63, v157
	v_fmac_f32_e32 v75, v63, v183
	v_fmac_f32_e32 v76, v63, v199
	v_fmac_f32_e32 v77, v63, v227
	v_fmac_f32_e32 v250, v63, v243
	v_fmac_f32_e32 v36, v60, v110
	v_fmac_f32_e32 v59, v60, v126
	v_fmac_f32_e32 v67, v60, v142
	v_fmac_f32_e32 v74, v60, v158
	v_fmac_f32_e32 v75, v60, v184
	v_fmac_f32_e32 v76, v60, v200
	v_fmac_f32_e32 v77, v60, v228
	v_fmac_f32_e32 v250, v60, v244
	v_fmac_f32_e32 v36, v61, v111
	v_fmac_f32_e32 v59, v61, v127
	v_fmac_f32_e32 v67, v61, v143
	v_fmac_f32_e32 v74, v61, v159
	v_fmac_f32_e32 v75, v61, v185
	v_fmac_f32_e32 v76, v61, v201
	v_fmac_f32_e32 v77, v61, v229
	v_fmac_f32_e32 v250, v61, v245
	v_fmac_f32_e32 v36, v222, v112
	v_fmac_f32_e32 v59, v222, v128
	v_fmac_f32_e32 v67, v222, v144
	v_fmac_f32_e32 v74, v222, v170
	v_fmac_f32_e32 v75, v222, v186
	v_fmac_f32_e32 v76, v222, v202
	v_fmac_f32_e32 v77, v222, v230
	v_fmac_f32_e32 v250, v222, v246
	v_fmac_f32_e32 v36, v223, v113
	v_fmac_f32_e32 v59, v223, v129
	v_fmac_f32_e32 v67, v223, v145
	v_fmac_f32_e32 v74, v223, v171
	v_fmac_f32_e32 v75, v223, v187
	v_fmac_f32_e32 v76, v223, v203
	v_fmac_f32_e32 v77, v223, v231
	v_fmac_f32_e32 v250, v223, v247
	v_fmac_f32_e32 v36, v220, v114
	v_fmac_f32_e32 v59, v220, v130
	v_fmac_f32_e32 v67, v220, v146
	v_fmac_f32_e32 v74, v220, v172
	v_fmac_f32_e32 v75, v220, v188
	v_fmac_f32_e32 v76, v220, v204
	v_fmac_f32_e32 v77, v220, v232
	v_fmac_f32_e32 v250, v220, v248
	v_fmac_f32_e32 v36, v221, v115
	v_fmac_f32_e32 v59, v221, v131
	v_fmac_f32_e32 v67, v221, v147
	v_fmac_f32_e32 v74, v221, v173
	v_fmac_f32_e32 v75, v221, v189
	v_fmac_f32_e32 v76, v221, v205
	v_fmac_f32_e32 v77, v221, v233
	v_fmac_f32_e32 v250, v221, v249
	v_mov_b32_e32 v60, v250
	v_mov_b32_e32 v61, 0
	s_waitcnt lgkmcnt(0)
	v_add_f32_e32 v60, v60, v61
	v_add_f32_dpp v62, v36, v36 quad_perm:[1,0,3,2] row_mask:0xf bank_mask:0xf
	v_add_f32_dpp v63, v59, v59 quad_perm:[1,0,3,2] row_mask:0xf bank_mask:0xf
	v_add_f32_dpp v78, v67, v67 quad_perm:[1,0,3,2] row_mask:0xf bank_mask:0xf
	v_add_f32_dpp v79, v74, v74 quad_perm:[1,0,3,2] row_mask:0xf bank_mask:0xf
	v_add_f32_dpp v80, v75, v75 quad_perm:[1,0,3,2] row_mask:0xf bank_mask:0xf
	v_add_f32_dpp v81, v76, v76 quad_perm:[1,0,3,2] row_mask:0xf bank_mask:0xf
	v_add_f32_dpp v82, v77, v77 quad_perm:[1,0,3,2] row_mask:0xf bank_mask:0xf
	v_add_f32_dpp v61, v60, v60 quad_perm:[1,0,3,2] row_mask:0xf bank_mask:0xf
	v_add_f32_dpp v36, v62, v62 quad_perm:[2,3,0,1] row_mask:0xf bank_mask:0xf
	v_add_f32_dpp v59, v63, v63 quad_perm:[2,3,0,1] row_mask:0xf bank_mask:0xf
	v_add_f32_dpp v67, v78, v78 quad_perm:[2,3,0,1] row_mask:0xf bank_mask:0xf
	v_add_f32_dpp v74, v79, v79 quad_perm:[2,3,0,1] row_mask:0xf bank_mask:0xf
	v_add_f32_dpp v75, v80, v80 quad_perm:[2,3,0,1] row_mask:0xf bank_mask:0xf
	v_add_f32_dpp v76, v81, v81 quad_perm:[2,3,0,1] row_mask:0xf bank_mask:0xf
	v_add_f32_dpp v77, v82, v82 quad_perm:[2,3,0,1] row_mask:0xf bank_mask:0xf
	v_add_f32_dpp v60, v61, v61 quad_perm:[2,3,0,1] row_mask:0xf bank_mask:0xf
	v_add_f32_dpp v62, v36, v36 row_half_mirror row_mask:0xf bank_mask:0xf
	v_add_f32_dpp v63, v59, v59 row_half_mirror row_mask:0xf bank_mask:0xf
	v_add_f32_dpp v78, v67, v67 row_half_mirror row_mask:0xf bank_mask:0xf
	v_add_f32_dpp v79, v74, v74 row_half_mirror row_mask:0xf bank_mask:0xf
	v_add_f32_dpp v80, v75, v75 row_half_mirror row_mask:0xf bank_mask:0xf
	v_add_f32_dpp v81, v76, v76 row_half_mirror row_mask:0xf bank_mask:0xf
	v_add_f32_dpp v82, v77, v77 row_half_mirror row_mask:0xf bank_mask:0xf
	v_add_f32_dpp v61, v60, v60 row_half_mirror row_mask:0xf bank_mask:0xf
	v_add_f32_dpp v36, v62, v62 row_mirror row_mask:0xf bank_mask:0xf
	v_add_f32_dpp v59, v63, v63 row_mirror row_mask:0xf bank_mask:0xf
	v_add_f32_dpp v67, v78, v78 row_mirror row_mask:0xf bank_mask:0xf
	v_add_f32_dpp v74, v79, v79 row_mirror row_mask:0xf bank_mask:0xf
	v_add_f32_dpp v75, v80, v80 row_mirror row_mask:0xf bank_mask:0xf
	v_add_f32_dpp v76, v81, v81 row_mirror row_mask:0xf bank_mask:0xf
	v_add_f32_dpp v77, v82, v82 row_mirror row_mask:0xf bank_mask:0xf
	v_add_f32_dpp v60, v61, v61 row_mirror row_mask:0xf bank_mask:0xf
	v_mov_b32_e32 v62, v36
	v_mov_b32_e32 v63, v59
	v_mov_b32_e32 v78, v67
	v_mov_b32_e32 v79, v74
	v_mov_b32_e32 v80, v75
	v_mov_b32_e32 v81, v76
	v_mov_b32_e32 v82, v77
	v_mov_b32_e32 v61, v60
	v_permlane16_swap_b32_e32 v62, v36
	v_permlane16_swap_b32_e32 v63, v59
	v_permlane16_swap_b32_e32 v78, v67
	v_permlane16_swap_b32_e32 v79, v74
	v_permlane16_swap_b32_e32 v80, v75
	v_permlane16_swap_b32_e32 v81, v76
	v_permlane16_swap_b32_e32 v82, v77
	v_permlane16_swap_b32_e32 v61, v60
	v_add_f32_e32 v62, v62, v36
	v_add_f32_e32 v63, v63, v59
	v_add_f32_e32 v78, v78, v67
	v_add_f32_e32 v79, v79, v74
	v_add_f32_e32 v80, v80, v75
	v_add_f32_e32 v81, v81, v76
	v_add_f32_e32 v82, v82, v77
	v_add_f32_e32 v61, v61, v60
	v_mov_b32_e32 v36, v62
; template <int LO, int HI> __global__ void __launch_bounds__(NWAVES * 64, 2) fox_fwd(Args args) {
;     ...
;             float mine = fl[0];
; #pragma unroll
;             for (int q = 1; q < 8; ++q) mine = (lane == q) ? fl[q] : mine;
;             { const float z = mine + bfv; const float ls = fminf(z, 0.f) - log1pf(__expf(-fabsf(z)));
; #pragma unroll
;               for (int k = 0; k < 4; ++k)
; #pragma unroll
;                   for (int e = 0; e < 4; ++e) lsq[k][e] = (r == 4 * k + e) ? ls : lsq[k][e]; }
;         }
	v_mov_b32_e32 v59, v63
	v_mov_b32_e32 v67, v78
	v_mov_b32_e32 v74, v79
	v_mov_b32_e32 v75, v80
	v_mov_b32_e32 v76, v81
	v_mov_b32_e32 v77, v82
	v_mov_b32_e32 v60, v61
	v_permlane32_swap_b32_e32 v36, v62
	v_permlane32_swap_b32_e32 v59, v63
	v_permlane32_swap_b32_e32 v67, v78
	v_permlane32_swap_b32_e32 v74, v79
	v_permlane32_swap_b32_e32 v75, v80
	v_permlane32_swap_b32_e32 v76, v81
	v_permlane32_swap_b32_e32 v77, v82
	v_permlane32_swap_b32_e32 v60, v61
	v_add_f32_e32 v36, v36, v62
	v_add_f32_e32 v59, v59, v63
	v_add_f32_e32 v62, v67, v78
	v_add_f32_e32 v63, v74, v79
	v_add_f32_e32 v67, v75, v80
	v_add_f32_e32 v74, v76, v81
	v_add_f32_e32 v75, v77, v82
	v_add_f32_e32 v60, v60, v61
	v_cndmask_b32_e64 v36, v36, v59, s[4:5]
	v_cndmask_b32_e64 v36, v36, v62, s[6:7]
	v_cndmask_b32_e64 v36, v36, v63, s[8:9]
	v_cndmask_b32_e64 v36, v36, v67, s[10:11]
	v_cndmask_b32_e64 v36, v36, v74, s[12:13]
	v_cndmask_b32_e64 v36, v36, v75, s[14:15]
	v_cndmask_b32_e64 v36, v36, v60, s[16:17]
	v_add_f32_e32 v36, v71, v36
	v_min_f32_e32 v67, 0, v36
	v_mul_f32_e64 v36, |v36|, s29
	v_exp_f32_e32 v36, v36
	v_lshl_add_u64 v[56:57], v[56:57], 0, s[40:41]
	v_add_f32_e32 v59, 1.0, v36
	v_add_f32_e32 v62, -1.0, v59
	v_frexp_mant_f32_e32 v63, v59
	v_cvt_f64_f32_e32 v[60:61], v59
	v_sub_f32_e32 v74, v62, v59
	v_frexp_exp_i32_f64_e32 v60, v[60:61]
	v_cmp_gt_f32_e32 vcc, s37, v63
	v_sub_f32_e32 v62, v36, v62
	v_add_f32_e32 v61, 1.0, v74
	v_subbrev_co_u32_e32 v60, vcc, 0, v60, vcc
	v_add_f32_e32 v61, v62, v61
	v_sub_u32_e32 v62, 0, v60
	v_ldexp_f32 v59, v59, v62
	v_ldexp_f32 v61, v61, v62
	v_add_f32_e32 v62, -1.0, v59
	v_add_f32_e32 v74, 1.0, v59
	v_add_f32_e32 v63, 1.0, v62
	v_add_f32_e32 v75, -1.0, v74
	v_sub_f32_e32 v63, v59, v63
	v_sub_f32_e32 v59, v59, v75
	v_add_f32_e32 v59, v61, v59
	v_add_f32_e32 v75, v61, v63
	v_add_f32_e32 v61, v74, v59
	v_rcp_f32_e32 v78, v61
	v_add_f32_e32 v63, v62, v75
	v_sub_f32_e32 v74, v61, v74
	v_sub_f32_e32 v59, v59, v74
	v_mul_f32_e32 v80, v63, v78
	v_mul_f32_e32 v74, v61, v80
	v_fma_f32 v76, v80, v61, -v74
	v_sub_f32_e32 v62, v63, v62
	v_fmac_f32_e32 v76, v80, v59
	v_sub_f32_e32 v79, v75, v62
	v_add_f32_e32 v62, v74, v76
	v_sub_f32_e32 v75, v63, v62
	v_mov_b32_e32 v77, v62
	v_pk_add_f32 v[62:63], v[62:63], v[74:75] neg_lo:[0,1] neg_hi:[0,1]
	v_cvt_f32_i32_e32 v60, v60
	v_pk_add_f32 v[62:63], v[62:63], v[76:77] neg_lo:[0,1] neg_hi:[0,1]
	v_cmp_neq_f32_e32 vcc, s46, v36
	v_add_f32_e32 v63, v79, v63
	v_add_f32_e32 v62, v62, v63
	v_add_f32_e32 v63, v75, v62
	v_mul_f32_e32 v77, v78, v63
	v_mul_f32_e32 v74, v61, v77
	v_fma_f32 v76, v77, v61, -v74
	v_sub_f32_e32 v75, v75, v63
	v_fmac_f32_e32 v76, v77, v59
	v_add_f32_e32 v79, v62, v75
	v_add_f32_e32 v81, v80, v77
	v_add_f32_e32 v62, v74, v76
	v_sub_f32_e32 v61, v81, v80
	v_sub_f32_e32 v75, v63, v62
	v_sub_f32_e32 v59, v77, v61
	v_mov_b32_e32 v77, v62
	v_pk_add_f32 v[62:63], v[62:63], v[74:75] neg_lo:[0,1] neg_hi:[0,1]
	s_nop 0
	v_pk_add_f32 v[62:63], v[62:63], v[76:77] neg_lo:[0,1] neg_hi:[0,1]
	s_nop 0
	v_add_f32_e32 v61, v79, v63
	v_add_f32_e32 v61, v62, v61
	v_add_f32_e32 v61, v75, v61
	v_mul_f32_e32 v61, v78, v61
	v_add_f32_e32 v59, v59, v61
	v_add_f32_e32 v61, v81, v59
	v_mul_f32_e32 v62, v61, v61
	v_sub_f32_e32 v74, v61, v81
	v_fmamk_f32 v75, v62, 0x3e9b6dac, v20
	v_ldexp_f32 v63, v61, 1
	v_sub_f32_e32 v74, v59, v74
	v_mul_f32_e32 v61, v61, v62
	v_fmaak_f32 v59, v62, v75, 0x3f2aaada
	v_ldexp_f32 v77, v74, 1
	v_pk_mul_f32 v[74:75], v[60:61], v[58:59]
	s_nop 0
	v_fma_f32 v62, v60, s36, -v74
	v_fmac_f32_e32 v62, 0xb102e308, v60
	v_pk_add_f32 v[60:61], v[74:75], v[62:63]
	v_mov_b32_e32 v76, v74
	v_sub_f32_e32 v59, v61, v63
	v_sub_f32_e32 v59, v75, v59
	v_add_f32_e32 v77, v77, v59
	v_pk_add_f32 v[78:79], v[60:61], v[74:75] neg_lo:[0,1] neg_hi:[0,1]
	v_pk_add_f32 v[74:75], v[60:61], v[76:77]
	v_mov_b32_e32 v63, v60
	v_mov_b32_e32 v79, v75
	v_pk_add_f32 v[82:83], v[62:63], v[78:79] neg_lo:[0,1] neg_hi:[0,1]
	v_pk_add_f32 v[62:63], v[62:63], v[78:79]
	v_mov_b32_e32 v81, v60
	v_pk_add_f32 v[78:79], v[62:63], v[60:61] op_sel:[1,0] op_sel_hi:[0,1] neg_lo:[0,1] neg_hi:[0,1]
	v_mov_b32_e32 v80, v77
	v_mov_b32_e32 v76, v75
	v_mov_b32_e32 v77, v63
	v_pk_mov_b32 v[60:61], v[60:61], v[78:79] op_sel:[1,0]
	v_pk_add_f32 v[74:75], v[74:75], v[78:79] op_sel_hi:[1,0] neg_lo:[0,1] neg_hi:[0,1]
	v_pk_add_f32 v[60:61], v[76:77], v[60:61] neg_lo:[0,1] neg_hi:[0,1]
	v_mov_b32_e32 v74, v82
	v_pk_add_f32 v[60:61], v[80:81], v[60:61] neg_lo:[0,1] neg_hi:[0,1]
	v_mov_b32_e32 v83, v63
	v_pk_add_f32 v[74:75], v[74:75], v[60:61]
	s_nop 0
	v_pk_add_f32 v[76:77], v[74:75], v[74:75] op_sel:[0,1] op_sel_hi:[1,0]
	s_nop 0
	v_pk_add_f32 v[62:63], v[62:63], v[76:77] op_sel:[1,0] op_sel_hi:[0,1]
	v_mov_b32_e32 v75, v62
	v_mov_b32_e32 v61, v76
	v_pk_add_f32 v[76:77], v[74:75], v[82:83] neg_lo:[0,1] neg_hi:[0,1]
	s_nop 0
	v_sub_f32_e32 v59, v74, v76
	v_pk_add_f32 v[60:61], v[60:61], v[76:77] neg_lo:[0,1] neg_hi:[0,1]
	v_sub_f32_e32 v59, v82, v59
	v_add_f32_e32 v59, v60, v59
	v_add_f32_e32 v59, v59, v61
	v_add_f32_e32 v59, v62, v59
	v_cndmask_b32_e32 v59, v64, v59, vcc
	v_cmp_ngt_f32_e32 vcc, -1.0, v36
	s_nop 1
	v_cndmask_b32_e32 v59, v65, v59, vcc
	v_cmp_neq_f32_e32 vcc, -1.0, v36
	s_nop 1
	v_cndmask_b32_e32 v59, v66, v59, vcc
	v_cmp_lt_f32_e64 vcc, |v36|, s47
	s_nop 1
	v_cndmask_b32_e32 v36, v59, v36, vcc
	v_sub_f32_e32 v36, v67, v36
	s_cselect_b64 vcc, -1, 0
	s_cmpk_eq_i32 s30, 0x1000
	v_cndmask_b32_e32 v37, v37, v36, vcc
	s_cselect_b64 vcc, -1, 0
	s_cmpk_eq_i32 s30, 0x2000
	v_cndmask_b32_e32 v21, v21, v36, vcc
	s_cselect_b64 vcc, -1, 0
	s_cmpk_eq_i32 s30, 0x3000
	v_cndmask_b32_e32 v30, v30, v36, vcc
	s_cselect_b64 vcc, -1, 0
	s_cmpk_eq_i32 s30, 0x4000
	v_cndmask_b32_e32 v31, v31, v36, vcc
	s_cselect_b64 vcc, -1, 0
	s_cmpk_eq_i32 s30, 0x5000
	v_cndmask_b32_e32 v32, v32, v36, vcc
	s_cselect_b64 vcc, -1, 0
	s_cmpk_eq_i32 s30, 0x6000
	v_cndmask_b32_e32 v33, v33, v36, vcc
	s_cselect_b64 vcc, -1, 0
	s_cmpk_eq_i32 s30, 0x7000
	v_cndmask_b32_e32 v26, v26, v36, vcc
	s_cselect_b64 vcc, -1, 0
	s_cmpk_eq_u32 s30, 0x8000
	v_cndmask_b32_e32 v27, v27, v36, vcc
	s_cselect_b64 vcc, -1, 0
	s_cmpk_eq_u32 s30, 0x9000
	v_cndmask_b32_e32 v28, v28, v36, vcc
	s_cselect_b64 vcc, -1, 0
	s_cmpk_eq_u32 s30, 0xa000
	v_cndmask_b32_e32 v29, v29, v36, vcc
	s_cselect_b64 vcc, -1, 0
	s_cmpk_eq_u32 s30, 0xb000
	v_cndmask_b32_e32 v22, v22, v36, vcc
	s_cselect_b64 vcc, -1, 0
	s_cmpk_eq_u32 s30, 0xc000
	v_cndmask_b32_e32 v23, v23, v36, vcc
	s_cselect_b64 vcc, -1, 0
	s_cmpk_eq_u32 s30, 0xd000
	v_cndmask_b32_e32 v24, v24, v36, vcc
	s_cselect_b64 vcc, -1, 0
	s_add_u32 s30, s30, 0x1000
	s_addc_u32 s31, s31, 0
	s_cmpk_eq_u32 s30, 0xe000
	v_cndmask_b32_e32 v25, v25, v36, vcc
	s_cbranch_scc0 .LBB0_131
; template <int LO, int HI> __global__ void __launch_bounds__(NWAVES * 64, 2) fox_fwd(Args args) {
;     ...
;         if (lane < 8) { f32x4* dst = (f32x4*)(LF + (size_t)(b * 8 + lane) * T + (m0 - b * T));
; #pragma unroll
;             for (int k = 0; k < 4; ++k) dst[k] = lsq[k]; }
	s_mov_b32 m0, s52
	v_cmp_gt_u32_e32 vcc, 8, v1
	s_and_saveexec_b64 s[4:5], vcc
	s_cbranch_execz .LBB0_134
	v_lshl_or_b32 v2, s44, 3, v1
	v_ashrrev_i32_e32 v3, 31, v2
	s_lshl_b32 s6, s44, 12
	v_lshlrev_b64 v[2:3], 14, v[2:3]
	s_sub_i32 s6, s28, s6
	v_lshl_add_u64 v[2:3], s[26:27], 0, v[2:3]
	s_ashr_i32 s7, s6, 31
	v_lshl_add_u64 v[2:3], s[6:7], 2, v[2:3]
	s_mov_b64 s[6:7], 0x100000
	v_lshl_add_u64 v[4:5], v[2:3], 0, s[6:7]
	v_add_co_u32_e32 v2, vcc, 0x100000, v2
	v_mov_b32_e32 v20, v37
	s_nop 0
	v_addc_co_u32_e32 v3, vcc, 0, v3, vcc
	global_store_dwordx4 v[2:3], v[18:21], off
	global_store_dwordx4 v[4:5], v[30:33], off offset:16
	global_store_dwordx4 v[4:5], v[26:29], off offset:32
	global_store_dwordx4 v[4:5], v[22:25], off offset:48
